# attention-A: software-pipelined per-row tile bodies (QK of next tile beside softmax, PV beside exp), per-lane bias tables read by b128, per-round tile-mask table, LDS-DMA issue between the two rows, e
# speedup vs baseline: 1.0102x; 1.0027x over previous
.LBB0_269:
	s_or_b64 exec, exec, s[4:5]
	s_add_u32 s18, s56, 0xc400000
	s_addc_u32 s19, s57, 0
	s_or_b32 s0, s12, 11
	s_min_u32 s0, s0, 0x78
	s_add_i32 s0, s0, 7
	s_lshl_b32 s1, s24, 7
	s_add_u32 s20, s20, s1
	s_addc_u32 s21, s21, 0
	s_add_u32 s24, s18, s1
	v_sub_u32_e64 v4, s29, 8 clamp
	s_addc_u32 s25, s19, 0
	s_or_b32 s1, s12, 4
	v_min_u32_e32 v4, 32, v4
	v_or_b32_e32 v8, s29, v231
	s_min_u32 s1, s1, s0
	v_sub_u32_e64 v9, v8, 8 clamp
	v_lshl_add_u32 v10, v251, 3, v4
	s_lshl_b32 s22, s1, 13
	s_or_b32 s1, s12, 5
	v_min_u32_e32 v9, 48, v9
	v_sub_u32_e32 v12, v10, v8
	s_min_u32 s0, s1, s0
	v_add_u32_e32 v11, 16, v9
	v_max_i32_e32 v12, -15, v12
	s_lshl_b32 s4, s0, 13
	v_cmp_ge_u32_e32 vcc, v10, v9
	v_cmp_lt_u32_e64 s[0:1], v10, v11
	v_add_u32_e32 v12, 15, v12
	v_min_u32_e32 v12, 30, v12
	s_and_b64 vcc, vcc, s[0:1]
	v_or_b32_e32 v13, 1, v10
	v_cndmask_b32_e32 v12, 31, v12, vcc
	v_cmp_ge_u32_e32 vcc, v13, v9
	v_cmp_lt_u32_e64 s[0:1], v13, v11
	v_sub_u32_e32 v13, v13, v8
	v_max_i32_e32 v13, -15, v13
	v_add_u32_e32 v13, 15, v13
	v_min_u32_e32 v13, 30, v13
	s_and_b64 vcc, vcc, s[0:1]
	v_or_b32_e32 v14, 2, v10
	v_cndmask_b32_e32 v13, 31, v13, vcc
	v_cmp_ge_u32_e32 vcc, v14, v9
	v_cmp_lt_u32_e64 s[0:1], v14, v11
	v_sub_u32_e32 v14, v14, v8
	v_max_i32_e32 v14, -15, v14
	v_add_u32_e32 v14, 15, v14
	v_min_u32_e32 v14, 30, v14
	s_and_b64 vcc, vcc, s[0:1]
	v_or_b32_e32 v15, 3, v10
	v_cndmask_b32_e32 v14, 31, v14, vcc
	v_cmp_ge_u32_e32 vcc, v15, v9
	v_cmp_lt_u32_e64 s[0:1], v15, v11
	v_sub_u32_e32 v15, v15, v8
	v_max_i32_e32 v15, -15, v15
	v_add_u32_e32 v15, 15, v15
	v_min_u32_e32 v15, 30, v15
	s_and_b64 vcc, vcc, s[0:1]
	v_or_b32_e32 v16, 4, v10
	v_cndmask_b32_e32 v15, 31, v15, vcc
	v_cmp_ge_u32_e32 vcc, v16, v9
	v_cmp_lt_u32_e64 s[0:1], v16, v11
	v_sub_u32_e32 v16, v16, v8
	v_max_i32_e32 v16, -15, v16
	v_add_u32_e32 v16, 15, v16
	v_min_u32_e32 v16, 30, v16
	s_and_b64 vcc, vcc, s[0:1]
	v_or_b32_e32 v17, 5, v10
	v_cndmask_b32_e32 v16, 31, v16, vcc
	v_cmp_ge_u32_e32 vcc, v17, v9
	v_cmp_lt_u32_e64 s[0:1], v17, v11
	v_sub_u32_e32 v17, v17, v8
	v_max_i32_e32 v17, -15, v17
	v_add_u32_e32 v17, 15, v17
	v_min_u32_e32 v17, 30, v17
	s_and_b64 vcc, vcc, s[0:1]
	v_or_b32_e32 v18, 6, v10
	v_cndmask_b32_e32 v17, 31, v17, vcc
	v_cmp_ge_u32_e32 vcc, v18, v9
	v_cmp_lt_u32_e64 s[0:1], v18, v11
	v_sub_u32_e32 v18, v18, v8
	v_max_i32_e32 v18, -15, v18
	v_add_u32_e32 v18, 15, v18
	v_min_u32_e32 v18, 30, v18
	s_and_b64 vcc, vcc, s[0:1]
	v_or_b32_e32 v10, 7, v10
	v_cndmask_b32_e32 v18, 31, v18, vcc
	v_cmp_ge_u32_e32 vcc, v10, v9
	v_cmp_lt_u32_e64 s[0:1], v10, v11
	s_and_b64 vcc, vcc, s[0:1]
	s_add_i32 s0, s28, 0x200
	s_ashr_i32 s1, s0, 31
	s_add_u32 s0, s26, s0
	s_addc_u32 s1, s27, s1
	s_lshl_b64 s[0:1], s[0:1], 7
	s_add_u32 s0, s10, s0
	s_addc_u32 s1, s11, s1
	v_lshl_add_u64 v[252:253], s[0:1], 0, v[2:3]
	s_add_i32 s0, s28, 0x240
	s_ashr_i32 s1, s0, 31
	s_add_u32 s0, s26, s0
	s_addc_u32 s1, s27, s1
	s_lshl_b64 s[0:1], s[0:1], 7
	s_add_u32 s0, s10, s0
	s_addc_u32 s1, s11, s1
	v_lshl_add_u64 v[210:211], s[0:1], 0, v[2:3]
	s_add_i32 s0, s28, 0x280
	s_ashr_i32 s1, s0, 31
	s_add_u32 s0, s26, s0
	s_addc_u32 s1, s27, s1
	s_lshl_b64 s[0:1], s[0:1], 7
	s_add_u32 s0, s10, s0
	s_addc_u32 s1, s11, s1
	s_addk_i32 s28, 0x2c0
	v_lshl_add_u64 v[214:215], s[0:1], 0, v[2:3]
	s_ashr_i32 s1, s28, 31
	v_lshrrev_b32_e32 v6, 2, v231
	s_add_u32 s0, s26, s28
	v_lshl_add_u32 v7, v6, 3, v4
	v_sub_u32_e32 v8, v10, v8
	v_and_b32_e32 v9, 3, v5
	s_addc_u32 s1, s27, s1
	v_max_i32_e32 v8, -15, v8
	v_or_b32_e32 v7, v7, v9
	v_lshlrev_b32_e32 v234, 11, v6
	v_lshrrev_b32_e32 v6, 2, v5
	v_lshlrev_b32_e32 v5, 1, v5
	s_lshl_b64 s[0:1], s[0:1], 7
	v_add_u32_e32 v8, 15, v8
	v_lshrrev_b32_e32 v10, 1, v7
	v_lshlrev_b32_e32 v11, 1, v251
	v_and_b32_e32 v6, 2, v6
	v_and_b32_e32 v5, 4, v5
	s_add_u32 s0, s10, s0
	s_mov_b32 s23, 0
	v_min_u32_e32 v8, 30, v8
	v_bitop3_b32 v19, v10, v11, 5 bitop3:0x6c
	v_or_b32_e32 v11, 1, v11
	v_lshrrev_b32_e32 v4, 3, v4
	v_add3_u32 v5, v6, v251, v5
	s_addc_u32 s1, s11, s1
	s_mov_b32 s5, s23
	v_cndmask_b32_e32 v8, 31, v8, vcc
	v_bitop3_b32 v10, v10, v11, 5 bitop3:0x6c
	v_add_lshl_u32 v4, v5, v4, 4
	v_lshl_add_u64 v[218:219], s[0:1], 0, v[2:3]
	v_lshlrev_b32_e32 v235, 4, v19
	v_lshlrev_b32_e32 v236, 7, v9
	v_lshlrev_b32_e32 v237, 7, v7
	v_lshlrev_b32_e32 v238, 4, v10
	v_and_b32_e32 v239, 0x70, v4
	v_lshl_add_u64 v[232:233], v[252:253], 0, 16
	v_lshl_add_u64 v[212:213], v[210:211], 0, 16
	v_lshl_add_u64 v[216:217], v[214:215], 0, 16
	v_lshl_add_u64 v[220:221], v[218:219], 0, 16
	v_lshl_add_u64 v[222:223], v[202:203], 0, s[22:23]
	v_lshl_add_u64 v[224:225], v[204:205], 0, s[22:23]
	v_lshl_add_u64 v[226:227], v[202:203], 0, s[4:5]
	v_lshl_add_u64 v[228:229], v[204:205], 0, s[4:5]
	s_mov_b64 s[10:11], -1
	s_add_i32 s34, s13, 0x400
	s_add_i32 s35, s13, 0x800
	s_add_i32 s36, s13, 0xc00
	s_add_i32 s37, s13, 0x1000
	s_add_i32 s38, s13, 0x1400
	s_add_i32 s39, s13, 0x1800
	s_add_i32 s40, s13, 0x1c00
	s_add_i32 s46, 0, 0x20000
	s_mov_b32 s4, 0x3f803f80
	v_mov_b32_e32 v2, 0
	v_lshlrev_b32_e32 v240, 2, v12
	v_lshlrev_b32_e32 v241, 2, v16
	v_lshlrev_b32_e32 v242, 2, v13
	v_lshlrev_b32_e32 v243, 2, v17
	v_lshlrev_b32_e32 v244, 2, v14
	v_lshlrev_b32_e32 v245, 2, v18
	v_lshlrev_b32_e32 v246, 2, v15
	v_lshlrev_b32_e32 v247, 2, v8
	v_mbcnt_hi_u32_b32 v230, -1, v1
	v_mov_b32_e32 v6, 0x3f803f80
	s_mov_b32 s43, 0
	s_mov_b32 s5, 0
	v_readfirstlane_b32 s51, v0
	v_readlane_b32 s10, v255, 8
	v_readlane_b32 s11, v255, 9
	s_lshr_b32 s51, s51, 6
	s_and_b32 s53, s51, 3
	s_lshr_b32 s54, s51, 2
	s_lshl_b32 s55, s53, 4
	s_sub_i32 s55, s55, 8
	s_max_i32 s55, s55, 0
	s_min_i32 s55, s55, 32
	s_bfe_u32 s0, s52, 0x40003
	s_lshr_b32 s1, s52, 7
	s_add_i32 s5, s0, 16
	s_lshl_b32 s5, s5, 14
	s_lshl_b32 s6, s1, 13
	s_add_i32 s6, s5, s6
	s_mov_b32 s7, 0
	s_lshl_b64 s[6:7], s[6:7], 7
	s_add_u32 s26, s10, s6
	s_addc_u32 s27, s11, s7
	s_add_u32 s26, s26, 0x4400000
	s_addc_u32 s27, s27, 0
	s_lshl_b32 s5, s0, 14
	s_lshl_b32 s6, s1, 13
	s_add_i32 s6, s5, s6
	s_mov_b32 s7, 0
	s_lshl_b64 s[6:7], s[6:7], 7
	s_add_u32 s30, s10, s6
	s_addc_u32 s31, s11, s7
	s_add_u32 s30, s30, 0x4400000
	s_addc_u32 s31, s31, 0
	s_lshl_b32 s5, s0, 8
	s_lshl_b32 s6, s1, 7
	s_add_i32 s6, s5, s6
	s_mov_b32 s7, 0
	s_lshl_b64 s[6:7], s[6:7], 13
	s_add_u32 s28, s10, s6
	s_addc_u32 s29, s11, s7
	s_add_u32 s28, s28, 0xa400000
	s_addc_u32 s29, s29, 0
	s_lshl_b32 s5, s0, 7
	s_lshl_b32 s6, s53, 15
	s_add_i32 s5, s5, s6
	s_lshl_b32 s6, s1, 24
	s_add_i32 s5, s5, s6
	s_add_u32 s56, s10, s5
	s_addc_u32 s57, s11, 0
	s_add_u32 s56, s56, 0x8400000
	s_addc_u32 s57, s57, 0
	s_add_u32 s58, s10, s5
	s_addc_u32 s59, s11, 0
	s_add_u32 s58, s58, 0xc400000
	s_addc_u32 s59, s59, 0
	s_mul_i32 s64, s51, 0x2400
	s_add_i32 s64, s64, 0x10000
	s_cmp_eq_u32 s51, 7
	s_cselect_b32 s64, 0x21000, s64
	s_xor_b32 s0, s51, 4
	s_mul_i32 s32, s0, 0x2400
	s_add_i32 s32, s32, 0x10000
	s_cmp_eq_u32 s0, 7
	s_cselect_b32 s32, 0x21000, s32
	v_and_b32_e32 v1, 63, v0
	v_and_b32_e32 v3, 15, v1
	v_lshrrev_b32_e32 v4, 4, v1
	v_lshlrev_b32_e32 v197, 4, v1
	v_lshrrev_b32_e32 v5, 2, v3
	v_and_b32_e32 v7, 3, v3
	v_lshl_add_u32 v198, v5, 3, v7
	v_add_u32_e32 v198, s55, v198
	v_bfe_u32 v199, v198, 1, 1
	v_bfe_u32 v200, v198, 3, 1
	v_lshl_or_b32 v199, v200, 2, v199
	v_lshlrev_b32_e32 v200, 1, v4
	v_xor_b32_e32 v201, v200, v199
	v_lshlrev_b32_e32 v201, 4, v201
	v_lshl_add_u32 v188, v198, 7, v201
	v_or_b32_e32 v200, 1, v200
	v_xor_b32_e32 v201, v200, v199
	v_lshlrev_b32_e32 v201, 4, v201
	v_lshl_add_u32 v189, v198, 7, v201
	v_lshl_add_u32 v198, v5, 4, v7
	v_bfe_u32 v199, v198, 5, 1
	v_bfe_u32 v200, v198, 1, 1
	v_lshlrev_b32_e32 v199, 1, v199
	v_lshl_add_u32 v199, v200, 2, v199
	v_add_u32_e32 v199, v199, v4
	s_lshr_b32 s0, s55, 3
	v_add_u32_e32 v199, s0, v199
	v_and_b32_e32 v199, 7, v199
	v_lshlrev_b32_e32 v199, 4, v199
	v_lshl_add_u32 v190, v198, 7, v199
	v_add_u32_e32 v190, 0x2000, v190
	v_lshrrev_b32_e32 v198, 3, v1
	s_lshl_b32 s0, s51, 3
	v_add_u32_e32 v198, s0, v198
	v_and_b32_e32 v199, 7, v1
	v_bfe_u32 v200, v198, 1, 1
	v_bfe_u32 v201, v198, 3, 1
	v_lshl_or_b32 v201, v201, 2, v200
	v_xor_b32_e32 v201, v199, v201
	v_lshlrev_b32_e32 v201, 4, v201
	v_lshl_add_u32 v191, v198, 7, v201
	v_bfe_u32 v201, v198, 5, 1
	v_lshlrev_b32_e32 v201, 1, v201
	v_lshl_add_u32 v201, v200, 2, v201
	v_sub_u32_e32 v201, v199, v201
	v_and_b32_e32 v201, 7, v201
	v_lshlrev_b32_e32 v201, 4, v201
	v_lshl_add_u32 v192, v198, 7, v201
	v_lshlrev_b32_e32 v198, 5, v4
	v_lshl_add_u32 v193, v3, 7, v198
	v_lshl_add_u32 v196, v3, 11, v198
	v_xor_b32_e32 v198, 16, v1
	v_lshlrev_b32_e32 v194, 2, v198
	v_xor_b32_e32 v198, 32, v1
	v_lshlrev_b32_e32 v195, 2, v198
	s_lshl_b32 s0, s53, 4
	v_add_u32_e32 v5, s0, v3
	v_sub_u32_e64 v7, v5, 8 clamp
	v_min_u32_e32 v7, 48, v7
	v_add_u32_e32 v198, 16, v7
	v_lshlrev_b32_e32 v199, 3, v4
	v_add_u32_e32 v199, s55, v199
	v_add_u32_e32 v200, 0, v199
	v_sub_u32_e32 v201, v200, v5
	v_add_u32_e32 v201, 15, v201
	v_max_i32_e32 v201, 0, v201
	v_min_i32_e32 v201, 30, v201
	v_cmp_ge_u32_e32 vcc, v200, v7
	v_cmp_lt_u32_e64 s[0:1], v200, v198
	s_and_b64 vcc, vcc, s[0:1]
	v_mov_b32_e32 v206, 31
	v_cndmask_b32_e32 v201, v206, v201, vcc
	v_lshlrev_b32_e32 v201, 2, v201
	v_add_u32_e32 v180, 0x20000, v201
	v_add_u32_e32 v200, 1, v199
	v_sub_u32_e32 v201, v200, v5
	v_add_u32_e32 v201, 15, v201
	v_max_i32_e32 v201, 0, v201
	v_min_i32_e32 v201, 30, v201
	v_cmp_ge_u32_e32 vcc, v200, v7
	v_cmp_lt_u32_e64 s[0:1], v200, v198
	s_and_b64 vcc, vcc, s[0:1]
	v_mov_b32_e32 v206, 31
	v_cndmask_b32_e32 v201, v206, v201, vcc
	v_lshlrev_b32_e32 v201, 2, v201
	v_add_u32_e32 v181, 0x20000, v201
	v_add_u32_e32 v200, 2, v199
	v_sub_u32_e32 v201, v200, v5
	v_add_u32_e32 v201, 15, v201
	v_max_i32_e32 v201, 0, v201
	v_min_i32_e32 v201, 30, v201
	v_cmp_ge_u32_e32 vcc, v200, v7
	v_cmp_lt_u32_e64 s[0:1], v200, v198
	s_and_b64 vcc, vcc, s[0:1]
	v_mov_b32_e32 v206, 31
	v_cndmask_b32_e32 v201, v206, v201, vcc
	v_lshlrev_b32_e32 v201, 2, v201
	v_add_u32_e32 v182, 0x20000, v201
	v_add_u32_e32 v200, 3, v199
	v_sub_u32_e32 v201, v200, v5
	v_add_u32_e32 v201, 15, v201
	v_max_i32_e32 v201, 0, v201
	v_min_i32_e32 v201, 30, v201
	v_cmp_ge_u32_e32 vcc, v200, v7
	v_cmp_lt_u32_e64 s[0:1], v200, v198
	s_and_b64 vcc, vcc, s[0:1]
	v_mov_b32_e32 v206, 31
	v_cndmask_b32_e32 v201, v206, v201, vcc
	v_lshlrev_b32_e32 v201, 2, v201
	v_add_u32_e32 v183, 0x20000, v201
	v_add_u32_e32 v200, 4, v199
	v_sub_u32_e32 v201, v200, v5
	v_add_u32_e32 v201, 15, v201
	v_max_i32_e32 v201, 0, v201
	v_min_i32_e32 v201, 30, v201
	v_cmp_ge_u32_e32 vcc, v200, v7
	v_cmp_lt_u32_e64 s[0:1], v200, v198
	s_and_b64 vcc, vcc, s[0:1]
	v_mov_b32_e32 v206, 31
	v_cndmask_b32_e32 v201, v206, v201, vcc
	v_lshlrev_b32_e32 v201, 2, v201
	v_add_u32_e32 v184, 0x20000, v201
	v_add_u32_e32 v200, 5, v199
	v_sub_u32_e32 v201, v200, v5
	v_add_u32_e32 v201, 15, v201
	v_max_i32_e32 v201, 0, v201
	v_min_i32_e32 v201, 30, v201
	v_cmp_ge_u32_e32 vcc, v200, v7
	v_cmp_lt_u32_e64 s[0:1], v200, v198
	s_and_b64 vcc, vcc, s[0:1]
	v_mov_b32_e32 v206, 31
	v_cndmask_b32_e32 v201, v206, v201, vcc
	v_lshlrev_b32_e32 v201, 2, v201
	v_add_u32_e32 v185, 0x20000, v201
	v_add_u32_e32 v200, 6, v199
	v_sub_u32_e32 v201, v200, v5
	v_add_u32_e32 v201, 15, v201
	v_max_i32_e32 v201, 0, v201
	v_min_i32_e32 v201, 30, v201
	v_cmp_ge_u32_e32 vcc, v200, v7
	v_cmp_lt_u32_e64 s[0:1], v200, v198
	s_and_b64 vcc, vcc, s[0:1]
	v_mov_b32_e32 v206, 31
	v_cndmask_b32_e32 v201, v206, v201, vcc
	v_lshlrev_b32_e32 v201, 2, v201
	v_add_u32_e32 v186, 0x20000, v201
	v_add_u32_e32 v200, 7, v199
	v_sub_u32_e32 v201, v200, v5
	v_add_u32_e32 v201, 15, v201
	v_max_i32_e32 v201, 0, v201
	v_min_i32_e32 v201, 30, v201
	v_cmp_ge_u32_e32 vcc, v200, v7
	v_cmp_lt_u32_e64 s[0:1], v200, v198
	s_and_b64 vcc, vcc, s[0:1]
	v_mov_b32_e32 v206, 31
	v_cndmask_b32_e32 v201, v206, v201, vcc
	v_lshlrev_b32_e32 v201, 2, v201
	v_add_u32_e32 v187, 0x20000, v201
	v_mov_b32_e32 v176, 0x3f803f80
	v_mov_b32_e32 v177, 0x3f803f80
	v_mov_b32_e32 v178, 0x3f803f80
	v_mov_b32_e32 v179, 0x3f803f80
	s_mov_b32 s62, 0
	s_mov_b32 s63, 0
	s_lshl_b32 s41, s52, 4
	s_and_b32 s41, s41, 0x70
	s_add_i32 s42, s41, -4
	s_max_i32 s42, s42, 0
	s_min_i32 s42, s42, 0x78
	s_add_i32 s43, s41, 3
	s_max_i32 s43, s43, 0
	s_min_i32 s43, s43, 0x78
	s_add_i32 s43, s43, 7
	s_sub_i32 s45, s43, s42
	s_add_i32 s45, s45, 2
	s_lshr_b32 s45, s45, 1
	s_add_i32 s47, s41, s54
	s_add_i32 s47, s47, -4
	s_max_i32 s47, s47, 0
	s_min_i32 s47, s47, 0x78
	s_add_i32 s48, s41, s54
	s_add_i32 s48, s48, -2
	s_max_i32 s48, s48, 0
	s_min_i32 s48, s48, 0x78
	s_add_i32 s49, s41, s54
	s_add_i32 s49, s49, 0
	s_max_i32 s49, s49, 0
	s_min_i32 s49, s49, 0x78
	s_add_i32 s50, s41, s54
	s_add_i32 s50, s50, 2
	s_max_i32 s50, s50, 0
	s_min_i32 s50, s50, 0x78
	s_add_i32 s5, s41, s54
	s_add_i32 s5, s5, 0
	s_lshl_b32 s5, s5, 6
	s_lshl_b32 s6, s53, 4
	s_add_i32 s5, s5, s6
	s_lshl_b32 s5, s5, 7
	s_add_u32 s0, s30, s5
	s_addc_u32 s1, s31, 0
	global_load_dwordx4 v[92:95], v193, s[0:1]
	global_load_dwordx4 v[96:99], v193, s[0:1] offset:16
	s_add_i32 s5, s41, s54
	s_add_i32 s5, s5, 2
	s_lshl_b32 s5, s5, 6
	s_lshl_b32 s6, s53, 4
	s_add_i32 s5, s5, s6
	s_lshl_b32 s5, s5, 7
	s_add_u32 s0, s30, s5
	s_addc_u32 s1, s31, 0
	global_load_dwordx4 v[100:103], v193, s[0:1]
	global_load_dwordx4 v[104:107], v193, s[0:1] offset:16
	s_add_i32 s5, s41, s54
	s_add_i32 s5, s5, 4
	s_lshl_b32 s5, s5, 6
	s_lshl_b32 s6, s53, 4
	s_add_i32 s5, s5, s6
	s_lshl_b32 s5, s5, 7
	s_add_u32 s0, s30, s5
	s_addc_u32 s1, s31, 0
	global_load_dwordx4 v[108:111], v193, s[0:1]
	global_load_dwordx4 v[112:115], v193, s[0:1] offset:16
	s_add_i32 s5, s41, s54
	s_add_i32 s5, s5, 6
	s_lshl_b32 s5, s5, 6
	s_lshl_b32 s6, s53, 4
	s_add_i32 s5, s5, s6
	s_lshl_b32 s5, s5, 7
	s_add_u32 s0, s30, s5
	s_addc_u32 s1, s31, 0
	global_load_dwordx4 v[116:119], v193, s[0:1]
	global_load_dwordx4 v[120:123], v193, s[0:1] offset:16
	s_and_b32 s5, s62, 1
	s_lshl_b32 s5, s5, 15
	s_lshl_b32 s6, s51, 10
	s_add_i32 s5, s5, s6
	s_add_i32 s6, s42, 0
	s_min_i32 s6, s6, s43
	s_lshl_b32 s6, s6, 13
	s_add_u32 s0, s26, s6
	s_addc_u32 s1, s27, 0
	s_add_i32 m0, s5, 0x0
	s_nop 0
	global_load_lds_dwordx4 v191, s[0:1]
	s_add_u32 s0, s28, s6
	s_addc_u32 s1, s29, 0
	s_add_i32 m0, s5, 0x2000
	s_nop 0
	global_load_lds_dwordx4 v192, s[0:1]
	s_add_i32 s6, s42, 1
	s_min_i32 s6, s6, s43
	s_lshl_b32 s6, s6, 13
	s_add_u32 s0, s26, s6
	s_addc_u32 s1, s27, 0
	s_add_i32 m0, s5, 0x4000
	s_nop 0
	global_load_lds_dwordx4 v191, s[0:1]
	s_add_u32 s0, s28, s6
	s_addc_u32 s1, s29, 0
	s_add_i32 m0, s5, 0x6000
	s_nop 0
	global_load_lds_dwordx4 v192, s[0:1]
	s_waitcnt lgkmcnt(0)
	s_barrier
	s_add_i32 s0, s53, 1
	s_lshr_b32 s0, s0, 1
	s_mul_i32 s0, s0, 0x7800
	s_add_i32 s0, s0, 0x10000
	v_add_u32_e32 v250, s0, v197
	s_lshl_b32 s1, s54, 10
	v_add_u32_e32 v198, s1, v180
	v_add_u32_e32 v199, s1, v181
	v_add_u32_e32 v200, s1, v182
	v_add_u32_e32 v201, s1, v183
	v_add_u32_e32 v206, s1, v184
	v_add_u32_e32 v207, s1, v185
	v_add_u32_e32 v208, s1, v186
	v_add_u32_e32 v209, s1, v187
	s_lshl_b32 s1, s54, 14
	v_add_u32_e32 v248, s1, v250
	ds_read_b32 v124, v198 offset:0
	ds_read_b32 v125, v199 offset:0
	ds_read_b32 v126, v200 offset:0
	ds_read_b32 v127, v201 offset:0
	ds_read_b32 v128, v206 offset:0
	ds_read_b32 v129, v207 offset:0
	ds_read_b32 v130, v208 offset:0
	ds_read_b32 v131, v209 offset:0
	ds_read_b32 v132, v198 offset:128
	ds_read_b32 v133, v199 offset:128
	ds_read_b32 v134, v200 offset:128
	ds_read_b32 v135, v201 offset:128
	ds_read_b32 v136, v206 offset:128
	ds_read_b32 v137, v207 offset:128
	ds_read_b32 v138, v208 offset:128
	ds_read_b32 v139, v209 offset:128
	ds_read_b32 v140, v198 offset:256
	ds_read_b32 v141, v199 offset:256
	ds_read_b32 v142, v200 offset:256
	ds_read_b32 v143, v201 offset:256
	ds_read_b32 v144, v206 offset:256
	ds_read_b32 v145, v207 offset:256
	ds_read_b32 v146, v208 offset:256
	ds_read_b32 v147, v209 offset:256
	ds_read_b32 v148, v198 offset:384
	ds_read_b32 v149, v199 offset:384
	ds_read_b32 v150, v200 offset:384
	ds_read_b32 v151, v201 offset:384
	ds_read_b32 v152, v206 offset:384
	ds_read_b32 v153, v207 offset:384
	ds_read_b32 v154, v208 offset:384
	ds_read_b32 v155, v209 offset:384
	s_waitcnt lgkmcnt(0)
	ds_write_b128 v248, v[124:127] offset:0
	ds_write_b128 v248, v[128:131] offset:1024
	ds_write_b128 v248, v[132:135] offset:2048
	ds_write_b128 v248, v[136:139] offset:3072
	ds_write_b128 v248, v[148:151] offset:6144
	ds_write_b128 v248, v[152:155] offset:7168
	ds_read_b32 v156, v198 offset:512
	ds_read_b32 v157, v199 offset:512
	ds_read_b32 v158, v200 offset:512
	ds_read_b32 v159, v201 offset:512
	ds_read_b32 v160, v206 offset:512
	ds_read_b32 v161, v207 offset:512
	ds_read_b32 v162, v208 offset:512
	ds_read_b32 v163, v209 offset:512
	ds_read_b32 v164, v198 offset:640
	ds_read_b32 v165, v199 offset:640
	ds_read_b32 v166, v200 offset:640
	ds_read_b32 v167, v201 offset:640
	ds_read_b32 v168, v206 offset:640
	ds_read_b32 v169, v207 offset:640
	ds_read_b32 v170, v208 offset:640
	ds_read_b32 v171, v209 offset:640
	ds_read_b32 v232, v198 offset:768
	ds_read_b32 v233, v199 offset:768
	ds_read_b32 v234, v200 offset:768
	ds_read_b32 v235, v201 offset:768
	ds_read_b32 v236, v206 offset:768
	ds_read_b32 v237, v207 offset:768
	ds_read_b32 v238, v208 offset:768
	ds_read_b32 v239, v209 offset:768
	ds_read_b32 v240, v198 offset:896
	ds_read_b32 v241, v199 offset:896
	ds_read_b32 v242, v200 offset:896
	ds_read_b32 v243, v201 offset:896
	ds_read_b32 v244, v206 offset:896
	ds_read_b32 v245, v207 offset:896
	ds_read_b32 v246, v208 offset:896
	ds_read_b32 v247, v209 offset:896
	s_waitcnt lgkmcnt(0)
	ds_write_b128 v248, v[156:159] offset:8192
	ds_write_b128 v248, v[160:163] offset:9216
	ds_write_b128 v248, v[164:167] offset:10240
	ds_write_b128 v248, v[168:171] offset:11264
	ds_write_b128 v248, v[232:235] offset:12288
	ds_write_b128 v248, v[236:239] offset:13312
	s_cmp_eq_u32 s54, 0
	s_cbranch_scc0 .La0_bt_no15
	ds_write_b128 v248, v[240:243] offset:14336
	ds_write_b128 v248, v[244:247] offset:15360
.La0_bt_no15:
	s_waitcnt lgkmcnt(0)
	s_barrier
	ds_write_b128 v248, v[140:143] offset:4096
	ds_write_b128 v248, v[144:147] offset:5120
.La0_round:
	v_mov_b32_e32 v88, 0xf149f2ca
	v_mov_b32_e32 v72, 0
	v_mov_b32_e32 v73, 0
	v_mov_b32_e32 v74, 0
	v_mov_b32_e32 v75, 0
	v_mov_b32_e32 v8, 0
	v_mov_b32_e32 v9, 0
	v_mov_b32_e32 v10, 0
	v_mov_b32_e32 v11, 0
	v_mov_b32_e32 v12, 0
	v_mov_b32_e32 v13, 0
	v_mov_b32_e32 v14, 0
	v_mov_b32_e32 v15, 0
	v_mov_b32_e32 v16, 0
	v_mov_b32_e32 v17, 0
	v_mov_b32_e32 v18, 0
	v_mov_b32_e32 v19, 0
	v_mov_b32_e32 v20, 0
	v_mov_b32_e32 v21, 0
	v_mov_b32_e32 v22, 0
	v_mov_b32_e32 v23, 0
	v_mov_b32_e32 v89, 0xf149f2ca
	v_mov_b32_e32 v76, 0
	v_mov_b32_e32 v77, 0
	v_mov_b32_e32 v78, 0
	v_mov_b32_e32 v79, 0
	v_mov_b32_e32 v24, 0
	v_mov_b32_e32 v25, 0
	v_mov_b32_e32 v26, 0
	v_mov_b32_e32 v27, 0
	v_mov_b32_e32 v28, 0
	v_mov_b32_e32 v29, 0
	v_mov_b32_e32 v30, 0
	v_mov_b32_e32 v31, 0
	v_mov_b32_e32 v32, 0
	v_mov_b32_e32 v33, 0
	v_mov_b32_e32 v34, 0
	v_mov_b32_e32 v35, 0
	v_mov_b32_e32 v36, 0
	v_mov_b32_e32 v37, 0
	v_mov_b32_e32 v38, 0
	v_mov_b32_e32 v39, 0
	v_mov_b32_e32 v90, 0xf149f2ca
	v_mov_b32_e32 v80, 0
	v_mov_b32_e32 v81, 0
	v_mov_b32_e32 v82, 0
	v_mov_b32_e32 v83, 0
	v_mov_b32_e32 v40, 0
	v_mov_b32_e32 v41, 0
	v_mov_b32_e32 v42, 0
	v_mov_b32_e32 v43, 0
	v_mov_b32_e32 v44, 0
	v_mov_b32_e32 v45, 0
	v_mov_b32_e32 v46, 0
	v_mov_b32_e32 v47, 0
	v_mov_b32_e32 v48, 0
	v_mov_b32_e32 v49, 0
	v_mov_b32_e32 v50, 0
	v_mov_b32_e32 v51, 0
	v_mov_b32_e32 v52, 0
	v_mov_b32_e32 v53, 0
	v_mov_b32_e32 v54, 0
	v_mov_b32_e32 v55, 0
	v_mov_b32_e32 v91, 0xf149f2ca
	v_mov_b32_e32 v84, 0
	v_mov_b32_e32 v85, 0
	v_mov_b32_e32 v86, 0
	v_mov_b32_e32 v87, 0
	v_mov_b32_e32 v56, 0
	v_mov_b32_e32 v57, 0
	v_mov_b32_e32 v58, 0
	v_mov_b32_e32 v59, 0
	v_mov_b32_e32 v60, 0
	v_mov_b32_e32 v61, 0
	v_mov_b32_e32 v62, 0
	v_mov_b32_e32 v63, 0
	v_mov_b32_e32 v64, 0
	v_mov_b32_e32 v65, 0
	v_mov_b32_e32 v66, 0
	v_mov_b32_e32 v67, 0
	v_mov_b32_e32 v68, 0
	v_mov_b32_e32 v69, 0
	v_mov_b32_e32 v70, 0
	v_mov_b32_e32 v71, 0
	s_mov_b32 s44, 0
	s_mov_b64 s[100:101], 0
	s_sub_i32 s5, s47, s42
	s_lshl_b32 s5, s5, 2
	s_mov_b32 s0, 0x11111111
	s_mov_b32 s1, 0
	s_lshl_b64 s[0:1], s[0:1], s5
	s_or_b64 s[100:101], s[100:101], s[0:1]
	s_sub_i32 s5, s48, s42
	s_lshl_b32 s5, s5, 2
	s_add_i32 s5, s5, 1
	s_mov_b32 s0, 0x11111111
	s_mov_b32 s1, 0
	s_lshl_b64 s[0:1], s[0:1], s5
	s_or_b64 s[100:101], s[100:101], s[0:1]
	s_sub_i32 s5, s49, s42
	s_lshl_b32 s5, s5, 2
	s_add_i32 s5, s5, 2
	s_mov_b32 s0, 0x11111111
	s_mov_b32 s1, 0
	s_lshl_b64 s[0:1], s[0:1], s5
	s_or_b64 s[100:101], s[100:101], s[0:1]
	s_sub_i32 s5, s50, s42
	s_lshl_b32 s5, s5, 2
	s_add_i32 s5, s5, 3
	s_mov_b32 s0, 0x11111111
	s_mov_b32 s1, 0
	s_lshl_b64 s[0:1], s[0:1], s5
	s_or_b64 s[100:101], s[100:101], s[0:1]
.La0_ss:
	s_waitcnt vmcnt(0) lgkmcnt(0)
	s_barrier
	s_lshl_b32 s60, s44, 1
	s_add_i32 s60, s60, s42
	s_lshl_b32 s5, s44, 3
	s_lshr_b64 s[0:1], s[100:101], s5
	s_and_b32 s64, s0, 15
	s_bfe_u32 s32, s0, 0x40004
	s_and_b32 s61, s62, 1
	s_lshl_b32 s61, s61, 15
	s_cmp_eq_u32 s64, 0
	s_cbranch_scc1 .La0_noread0
	v_add_u32_e32 v207, s61, v188
	v_add_u32_e32 v208, s61, v189
	v_add_u32_e32 v209, s61, v190
	ds_read_b128 v[124:127], v207
	ds_read_b128 v[132:135], v207 offset:512
	ds_read_b128 v[128:131], v208
	ds_read_b128 v[136:139], v208 offset:512
	ds_read_b128 v[140:143], v209 offset:0
	ds_read_b128 v[144:147], v209 offset:512
	ds_read_b128 v[148:151], v209 offset:1024
	ds_read_b128 v[152:155], v209 offset:1536
.La0_noread0:
	s_cmp_eq_u32 s32, 0
	s_cbranch_scc1 .La0_noread1
	s_add_i32 s0, s61, 0x4000
	v_add_u32_e32 v207, s0, v188
	v_add_u32_e32 v208, s0, v189
	ds_read_b128 v[168:171], v207
	ds_read_b128 v[226:229], v207 offset:512
	ds_read_b128 v[172:175], v208
	ds_read_b128 v[244:247], v208 offset:512
.La0_noread1:
	s_lshl_b32 s60, s44, 1
	s_add_i32 s60, s60, s42
	s_cmp_eq_u32 s64, 0
	s_cbranch_scc1 .La0_rowdone_a
	s_sub_i32 s0, s60, s41
	s_sub_i32 s0, s0, s54
	s_add_i32 s0, s0, 1
	s_lshl_b32 s0, s0, 11
	v_add_u32_e32 v167, s0, v250
	s_cmp_eq_u32 s64, 15
	s_cbranch_scc1 .La0_pa_15
	s_cmp_eq_u32 s64, 7
	s_cbranch_scc1 .La0_pa_7
	s_cmp_eq_u32 s64, 14
	s_cbranch_scc1 .La0_pa_14
	s_cmp_eq_u32 s64, 3
	s_cbranch_scc1 .La0_pa_3
	s_cmp_eq_u32 s64, 12
	s_cbranch_scc1 .La0_pa_12
	s_cmp_eq_u32 s64, 1
	s_cbranch_scc1 .La0_pa_1
	s_cmp_eq_u32 s64, 8
	s_cbranch_scc1 .La0_pa_8
	s_branch .La0_rowdone_a
.La0_pa_15:
	ds_read_b128 v[156:159], v167 offset:12288
	ds_read_b128 v[160:163], v167 offset:13312
	ds_read_b128 v[232:235], v167 offset:8192
	ds_read_b128 v[236:239], v167 offset:9216
	ds_read_b128 v[180:183], v167 offset:4096
	ds_read_b128 v[184:187], v167 offset:5120
	ds_read_b128 v[198:201], v167 offset:0
	ds_read_b128 v[202:205], v167 offset:1024
	s_waitcnt lgkmcnt(6)
	v_mfma_f32_16x16x32_bf16 v[156:159], v[124:127], v[92:95], v[156:159]
	v_mfma_f32_16x16x32_bf16 v[160:163], v[132:135], v[92:95], v[160:163]
	v_mfma_f32_16x16x32_bf16 v[156:159], v[128:131], v[96:99], v[156:159]
	v_mfma_f32_16x16x32_bf16 v[160:163], v[136:139], v[96:99], v[160:163]
	s_waitcnt lgkmcnt(4)
	v_mfma_f32_16x16x32_bf16 v[232:235], v[124:127], v[100:103], v[232:235]
	v_mfma_f32_16x16x32_bf16 v[236:239], v[132:135], v[100:103], v[236:239]
	v_mfma_f32_16x16x32_bf16 v[232:235], v[128:131], v[104:107], v[232:235]
	v_mfma_f32_16x16x32_bf16 v[236:239], v[136:139], v[104:107], v[236:239]
	v_add_f32_e32 v164, 0x41000000, v88
	s_nop 3
	v_max3_f32 v165, v156, v157, v158
	v_max3_f32 v166, v159, v160, v161
	v_max3_f32 v165, v165, v162, v163
	v_max_f32_e32 v165, v165, v166
	v_cmp_gt_f32_e32 vcc, v165, v164
	s_cbranch_vccz .La0_nr_a15_0
	ds_bpermute_b32 v166, v194, v165
	s_waitcnt lgkmcnt(0)
	v_max_f32_e32 v165, v165, v166
	ds_bpermute_b32 v166, v195, v165
	s_waitcnt lgkmcnt(0)
	v_max3_f32 v165, v165, v166, v88
	v_sub_f32_e32 v166, v88, v165
	v_exp_f32_e32 v166, v166
	v_mov_b32_e32 v88, v165
	s_nop 0
	v_mul_f32_e32 v72, v72, v166
	v_mul_f32_e32 v73, v73, v166
	v_mul_f32_e32 v74, v74, v166
	v_mul_f32_e32 v75, v75, v166
	v_mul_f32_e32 v8, v8, v166
	v_mul_f32_e32 v9, v9, v166
	v_mul_f32_e32 v10, v10, v166
	v_mul_f32_e32 v11, v11, v166
	v_mul_f32_e32 v12, v12, v166
	v_mul_f32_e32 v13, v13, v166
	v_mul_f32_e32 v14, v14, v166
	v_mul_f32_e32 v15, v15, v166
	v_mul_f32_e32 v16, v16, v166
	v_mul_f32_e32 v17, v17, v166
	v_mul_f32_e32 v18, v18, v166
	v_mul_f32_e32 v19, v19, v166
	v_mul_f32_e32 v20, v20, v166
	v_mul_f32_e32 v21, v21, v166
	v_mul_f32_e32 v22, v22, v166
	v_mul_f32_e32 v23, v23, v166
.La0_nr_a15_0:
	v_sub_f32_e32 v156, v156, v88
	v_sub_f32_e32 v157, v157, v88
	v_sub_f32_e32 v158, v158, v88
	v_sub_f32_e32 v159, v159, v88
	v_sub_f32_e32 v160, v160, v88
	v_sub_f32_e32 v161, v161, v88
	v_sub_f32_e32 v162, v162, v88
	v_sub_f32_e32 v163, v163, v88
	v_exp_f32_e32 v156, v156
	v_exp_f32_e32 v157, v157
	v_exp_f32_e32 v158, v158
	v_exp_f32_e32 v159, v159
	v_exp_f32_e32 v160, v160
	v_exp_f32_e32 v161, v161
	v_exp_f32_e32 v162, v162
	v_exp_f32_e32 v163, v163
	s_nop 0
	v_cvt_pk_bf16_f32 v156, v156, v157
	v_cvt_pk_bf16_f32 v157, v158, v159
	v_cvt_pk_bf16_f32 v158, v160, v161
	v_cvt_pk_bf16_f32 v159, v162, v163
	s_waitcnt lgkmcnt(2)
	v_mfma_f32_16x16x32_bf16 v[180:183], v[124:127], v[108:111], v[180:183]
	v_add_f32_e32 v240, 0x41000000, v89
	v_max3_f32 v241, v232, v233, v234
	v_mfma_f32_16x16x32_bf16 v[184:187], v[132:135], v[108:111], v[184:187]
	v_max3_f32 v242, v235, v236, v237
	v_max3_f32 v241, v241, v238, v239
	v_mfma_f32_16x16x32_bf16 v[180:183], v[128:131], v[112:115], v[180:183]
	v_max_f32_e32 v241, v241, v242
	v_cmp_gt_f32_e32 vcc, v241, v240
	v_mfma_f32_16x16x32_bf16 v[184:187], v[136:139], v[112:115], v[184:187]
	s_cbranch_vccz .La0_nr_a15_1
	ds_bpermute_b32 v242, v194, v241
	s_waitcnt lgkmcnt(0)
	v_max_f32_e32 v241, v241, v242
	ds_bpermute_b32 v242, v195, v241
	s_waitcnt lgkmcnt(0)
	v_max3_f32 v241, v241, v242, v89
	v_sub_f32_e32 v242, v89, v241
	v_exp_f32_e32 v242, v242
	v_mov_b32_e32 v89, v241
	s_nop 0
	v_mul_f32_e32 v76, v76, v242
	v_mul_f32_e32 v77, v77, v242
	v_mul_f32_e32 v78, v78, v242
	v_mul_f32_e32 v79, v79, v242
	v_mul_f32_e32 v24, v24, v242
	v_mul_f32_e32 v25, v25, v242
	v_mul_f32_e32 v26, v26, v242
	v_mul_f32_e32 v27, v27, v242
	v_mul_f32_e32 v28, v28, v242
	v_mul_f32_e32 v29, v29, v242
	v_mul_f32_e32 v30, v30, v242
	v_mul_f32_e32 v31, v31, v242
	v_mul_f32_e32 v32, v32, v242
	v_mul_f32_e32 v33, v33, v242
	v_mul_f32_e32 v34, v34, v242
	v_mul_f32_e32 v35, v35, v242
	v_mul_f32_e32 v36, v36, v242
	v_mul_f32_e32 v37, v37, v242
	v_mul_f32_e32 v38, v38, v242
	v_mul_f32_e32 v39, v39, v242
.La0_nr_a15_1:
	v_mfma_f32_16x16x32_bf16 v[8:11], v[140:143], v[156:159], v[8:11]
	v_sub_f32_e32 v232, v232, v89
	v_sub_f32_e32 v233, v233, v89
	v_sub_f32_e32 v234, v234, v89
	v_sub_f32_e32 v235, v235, v89
	v_mfma_f32_16x16x32_bf16 v[12:15], v[144:147], v[156:159], v[12:15]
	v_sub_f32_e32 v236, v236, v89
	v_sub_f32_e32 v237, v237, v89
	v_sub_f32_e32 v238, v238, v89
	v_sub_f32_e32 v239, v239, v89
	v_mfma_f32_16x16x32_bf16 v[16:19], v[148:151], v[156:159], v[16:19]
	v_exp_f32_e32 v232, v232
	v_exp_f32_e32 v233, v233
	v_exp_f32_e32 v234, v234
	v_exp_f32_e32 v235, v235
	v_mfma_f32_16x16x32_bf16 v[20:23], v[152:155], v[156:159], v[20:23]
	v_exp_f32_e32 v236, v236
	v_exp_f32_e32 v237, v237
	v_exp_f32_e32 v238, v238
	v_exp_f32_e32 v239, v239
	v_mfma_f32_16x16x32_bf16 v[72:75], v[176:179], v[156:159], v[72:75]
	s_nop 0
	v_cvt_pk_bf16_f32 v232, v232, v233
	v_cvt_pk_bf16_f32 v233, v234, v235
	v_cvt_pk_bf16_f32 v234, v236, v237
	v_cvt_pk_bf16_f32 v235, v238, v239
	s_waitcnt lgkmcnt(0)
	v_mfma_f32_16x16x32_bf16 v[198:201], v[124:127], v[116:119], v[198:201]
	v_add_f32_e32 v1, 0x41000000, v90
	v_max3_f32 v3, v180, v181, v182
	v_mfma_f32_16x16x32_bf16 v[202:205], v[132:135], v[116:119], v[202:205]
	v_max3_f32 v4, v183, v184, v185
	v_max3_f32 v3, v3, v186, v187
	v_mfma_f32_16x16x32_bf16 v[198:201], v[128:131], v[120:123], v[198:201]
	v_max_f32_e32 v3, v3, v4
	v_cmp_gt_f32_e32 vcc, v3, v1
	v_mfma_f32_16x16x32_bf16 v[202:205], v[136:139], v[120:123], v[202:205]
	s_cbranch_vccz .La0_nr_a15_2
	ds_bpermute_b32 v4, v194, v3
	s_waitcnt lgkmcnt(0)
	v_max_f32_e32 v3, v3, v4
	ds_bpermute_b32 v4, v195, v3
	s_waitcnt lgkmcnt(0)
	v_max3_f32 v3, v3, v4, v90
	v_sub_f32_e32 v4, v90, v3
	v_exp_f32_e32 v4, v4
	v_mov_b32_e32 v90, v3
	s_nop 0
	v_mul_f32_e32 v80, v80, v4
	v_mul_f32_e32 v81, v81, v4
	v_mul_f32_e32 v82, v82, v4
	v_mul_f32_e32 v83, v83, v4
	v_mul_f32_e32 v40, v40, v4
	v_mul_f32_e32 v41, v41, v4
	v_mul_f32_e32 v42, v42, v4
	v_mul_f32_e32 v43, v43, v4
	v_mul_f32_e32 v44, v44, v4
	v_mul_f32_e32 v45, v45, v4
	v_mul_f32_e32 v46, v46, v4
	v_mul_f32_e32 v47, v47, v4
	v_mul_f32_e32 v48, v48, v4
	v_mul_f32_e32 v49, v49, v4
	v_mul_f32_e32 v50, v50, v4
	v_mul_f32_e32 v51, v51, v4
	v_mul_f32_e32 v52, v52, v4
	v_mul_f32_e32 v53, v53, v4
	v_mul_f32_e32 v54, v54, v4
	v_mul_f32_e32 v55, v55, v4
.La0_nr_a15_2:
	v_mfma_f32_16x16x32_bf16 v[24:27], v[140:143], v[232:235], v[24:27]
	v_sub_f32_e32 v180, v180, v90
	v_sub_f32_e32 v181, v181, v90
	v_sub_f32_e32 v182, v182, v90
	v_sub_f32_e32 v183, v183, v90
	v_mfma_f32_16x16x32_bf16 v[28:31], v[144:147], v[232:235], v[28:31]
	v_sub_f32_e32 v184, v184, v90
	v_sub_f32_e32 v185, v185, v90
	v_sub_f32_e32 v186, v186, v90
	v_sub_f32_e32 v187, v187, v90
	v_mfma_f32_16x16x32_bf16 v[32:35], v[148:151], v[232:235], v[32:35]
	v_exp_f32_e32 v180, v180
	v_exp_f32_e32 v181, v181
	v_exp_f32_e32 v182, v182
	v_exp_f32_e32 v183, v183
	v_mfma_f32_16x16x32_bf16 v[36:39], v[152:155], v[232:235], v[36:39]
	v_exp_f32_e32 v184, v184
	v_exp_f32_e32 v185, v185
	v_exp_f32_e32 v186, v186
	v_exp_f32_e32 v187, v187
	v_mfma_f32_16x16x32_bf16 v[76:79], v[176:179], v[232:235], v[76:79]
	s_nop 0
	v_cvt_pk_bf16_f32 v180, v180, v181
	v_cvt_pk_bf16_f32 v181, v182, v183
	v_cvt_pk_bf16_f32 v182, v184, v185
	v_cvt_pk_bf16_f32 v183, v186, v187
	v_add_f32_e32 v5, 0x41000000, v91
	v_max3_f32 v7, v198, v199, v200
	v_max3_f32 v206, v201, v202, v203
	v_max3_f32 v7, v7, v204, v205
	v_max_f32_e32 v7, v7, v206
	v_cmp_gt_f32_e32 vcc, v7, v5
	s_cbranch_vccz .La0_nr_a15_3
	ds_bpermute_b32 v206, v194, v7
	s_waitcnt lgkmcnt(0)
	v_max_f32_e32 v7, v7, v206
	ds_bpermute_b32 v206, v195, v7
	s_waitcnt lgkmcnt(0)
	v_max3_f32 v7, v7, v206, v91
	v_sub_f32_e32 v206, v91, v7
	v_exp_f32_e32 v206, v206
	v_mov_b32_e32 v91, v7
	s_nop 0
	v_mul_f32_e32 v84, v84, v206
	v_mul_f32_e32 v85, v85, v206
	v_mul_f32_e32 v86, v86, v206
	v_mul_f32_e32 v87, v87, v206
	v_mul_f32_e32 v56, v56, v206
	v_mul_f32_e32 v57, v57, v206
	v_mul_f32_e32 v58, v58, v206
	v_mul_f32_e32 v59, v59, v206
	v_mul_f32_e32 v60, v60, v206
	v_mul_f32_e32 v61, v61, v206
	v_mul_f32_e32 v62, v62, v206
	v_mul_f32_e32 v63, v63, v206
	v_mul_f32_e32 v64, v64, v206
	v_mul_f32_e32 v65, v65, v206
	v_mul_f32_e32 v66, v66, v206
	v_mul_f32_e32 v67, v67, v206
	v_mul_f32_e32 v68, v68, v206
	v_mul_f32_e32 v69, v69, v206
	v_mul_f32_e32 v70, v70, v206
	v_mul_f32_e32 v71, v71, v206
.La0_nr_a15_3:
	v_mfma_f32_16x16x32_bf16 v[40:43], v[140:143], v[180:183], v[40:43]
	v_sub_f32_e32 v198, v198, v91
	v_sub_f32_e32 v199, v199, v91
	v_sub_f32_e32 v200, v200, v91
	v_sub_f32_e32 v201, v201, v91
	v_mfma_f32_16x16x32_bf16 v[44:47], v[144:147], v[180:183], v[44:47]
	v_sub_f32_e32 v202, v202, v91
	v_sub_f32_e32 v203, v203, v91
	v_sub_f32_e32 v204, v204, v91
	v_sub_f32_e32 v205, v205, v91
	v_mfma_f32_16x16x32_bf16 v[48:51], v[148:151], v[180:183], v[48:51]
	v_exp_f32_e32 v198, v198
	v_exp_f32_e32 v199, v199
	v_exp_f32_e32 v200, v200
	v_exp_f32_e32 v201, v201
	v_mfma_f32_16x16x32_bf16 v[52:55], v[152:155], v[180:183], v[52:55]
	v_exp_f32_e32 v202, v202
	v_exp_f32_e32 v203, v203
	v_exp_f32_e32 v204, v204
	v_exp_f32_e32 v205, v205
	v_mfma_f32_16x16x32_bf16 v[80:83], v[176:179], v[180:183], v[80:83]
	s_nop 0
	v_cvt_pk_bf16_f32 v198, v198, v199
	v_cvt_pk_bf16_f32 v199, v200, v201
	v_cvt_pk_bf16_f32 v200, v202, v203
	v_cvt_pk_bf16_f32 v201, v204, v205
	s_nop 1
	v_mfma_f32_16x16x32_bf16 v[56:59], v[140:143], v[198:201], v[56:59]
	v_mfma_f32_16x16x32_bf16 v[60:63], v[144:147], v[198:201], v[60:63]
	v_mfma_f32_16x16x32_bf16 v[64:67], v[148:151], v[198:201], v[64:67]
	v_mfma_f32_16x16x32_bf16 v[68:71], v[152:155], v[198:201], v[68:71]
	v_mfma_f32_16x16x32_bf16 v[84:87], v[176:179], v[198:201], v[84:87]
	s_branch .La0_rowdone_a
.La0_pa_7:
	ds_read_b128 v[156:159], v167 offset:12288
	ds_read_b128 v[160:163], v167 offset:13312
	ds_read_b128 v[232:235], v167 offset:8192
	ds_read_b128 v[236:239], v167 offset:9216
	ds_read_b128 v[180:183], v167 offset:4096
	ds_read_b128 v[184:187], v167 offset:5120
	s_waitcnt lgkmcnt(4)
	v_mfma_f32_16x16x32_bf16 v[156:159], v[124:127], v[92:95], v[156:159]
	v_mfma_f32_16x16x32_bf16 v[160:163], v[132:135], v[92:95], v[160:163]
	v_mfma_f32_16x16x32_bf16 v[156:159], v[128:131], v[96:99], v[156:159]
	v_mfma_f32_16x16x32_bf16 v[160:163], v[136:139], v[96:99], v[160:163]
	s_waitcnt lgkmcnt(2)
	v_mfma_f32_16x16x32_bf16 v[232:235], v[124:127], v[100:103], v[232:235]
	v_mfma_f32_16x16x32_bf16 v[236:239], v[132:135], v[100:103], v[236:239]
	v_mfma_f32_16x16x32_bf16 v[232:235], v[128:131], v[104:107], v[232:235]
	v_mfma_f32_16x16x32_bf16 v[236:239], v[136:139], v[104:107], v[236:239]
	v_add_f32_e32 v164, 0x41000000, v88
	s_nop 3
	v_max3_f32 v165, v156, v157, v158
	v_max3_f32 v166, v159, v160, v161
	v_max3_f32 v165, v165, v162, v163
	v_max_f32_e32 v165, v165, v166
	v_cmp_gt_f32_e32 vcc, v165, v164
	s_cbranch_vccz .La0_nr_a7_0
	ds_bpermute_b32 v166, v194, v165
	s_waitcnt lgkmcnt(0)
	v_max_f32_e32 v165, v165, v166
	ds_bpermute_b32 v166, v195, v165
	s_waitcnt lgkmcnt(0)
	v_max3_f32 v165, v165, v166, v88
	v_sub_f32_e32 v166, v88, v165
	v_exp_f32_e32 v166, v166
	v_mov_b32_e32 v88, v165
	s_nop 0
	v_mul_f32_e32 v72, v72, v166
	v_mul_f32_e32 v73, v73, v166
	v_mul_f32_e32 v74, v74, v166
	v_mul_f32_e32 v75, v75, v166
	v_mul_f32_e32 v8, v8, v166
	v_mul_f32_e32 v9, v9, v166
	v_mul_f32_e32 v10, v10, v166
	v_mul_f32_e32 v11, v11, v166
	v_mul_f32_e32 v12, v12, v166
	v_mul_f32_e32 v13, v13, v166
	v_mul_f32_e32 v14, v14, v166
	v_mul_f32_e32 v15, v15, v166
	v_mul_f32_e32 v16, v16, v166
	v_mul_f32_e32 v17, v17, v166
	v_mul_f32_e32 v18, v18, v166
	v_mul_f32_e32 v19, v19, v166
	v_mul_f32_e32 v20, v20, v166
	v_mul_f32_e32 v21, v21, v166
	v_mul_f32_e32 v22, v22, v166
	v_mul_f32_e32 v23, v23, v166
.La0_nr_a7_0:
	v_sub_f32_e32 v156, v156, v88
	v_sub_f32_e32 v157, v157, v88
	v_sub_f32_e32 v158, v158, v88
	v_sub_f32_e32 v159, v159, v88
	v_sub_f32_e32 v160, v160, v88
	v_sub_f32_e32 v161, v161, v88
	v_sub_f32_e32 v162, v162, v88
	v_sub_f32_e32 v163, v163, v88
	v_exp_f32_e32 v156, v156
	v_exp_f32_e32 v157, v157
	v_exp_f32_e32 v158, v158
	v_exp_f32_e32 v159, v159
	v_exp_f32_e32 v160, v160
	v_exp_f32_e32 v161, v161
	v_exp_f32_e32 v162, v162
	v_exp_f32_e32 v163, v163
	s_nop 0
	v_cvt_pk_bf16_f32 v156, v156, v157
	v_cvt_pk_bf16_f32 v157, v158, v159
	v_cvt_pk_bf16_f32 v158, v160, v161
	v_cvt_pk_bf16_f32 v159, v162, v163
	s_waitcnt lgkmcnt(0)
	v_mfma_f32_16x16x32_bf16 v[180:183], v[124:127], v[108:111], v[180:183]
	v_add_f32_e32 v240, 0x41000000, v89
	v_max3_f32 v241, v232, v233, v234
	v_mfma_f32_16x16x32_bf16 v[184:187], v[132:135], v[108:111], v[184:187]
	v_max3_f32 v242, v235, v236, v237
	v_max3_f32 v241, v241, v238, v239
	v_mfma_f32_16x16x32_bf16 v[180:183], v[128:131], v[112:115], v[180:183]
	v_max_f32_e32 v241, v241, v242
	v_cmp_gt_f32_e32 vcc, v241, v240
	v_mfma_f32_16x16x32_bf16 v[184:187], v[136:139], v[112:115], v[184:187]
	s_cbranch_vccz .La0_nr_a7_1
	ds_bpermute_b32 v242, v194, v241
	s_waitcnt lgkmcnt(0)
	v_max_f32_e32 v241, v241, v242
	ds_bpermute_b32 v242, v195, v241
	s_waitcnt lgkmcnt(0)
	v_max3_f32 v241, v241, v242, v89
	v_sub_f32_e32 v242, v89, v241
	v_exp_f32_e32 v242, v242
	v_mov_b32_e32 v89, v241
	s_nop 0
	v_mul_f32_e32 v76, v76, v242
	v_mul_f32_e32 v77, v77, v242
	v_mul_f32_e32 v78, v78, v242
	v_mul_f32_e32 v79, v79, v242
	v_mul_f32_e32 v24, v24, v242
	v_mul_f32_e32 v25, v25, v242
	v_mul_f32_e32 v26, v26, v242
	v_mul_f32_e32 v27, v27, v242
	v_mul_f32_e32 v28, v28, v242
	v_mul_f32_e32 v29, v29, v242
	v_mul_f32_e32 v30, v30, v242
	v_mul_f32_e32 v31, v31, v242
	v_mul_f32_e32 v32, v32, v242
	v_mul_f32_e32 v33, v33, v242
	v_mul_f32_e32 v34, v34, v242
	v_mul_f32_e32 v35, v35, v242
	v_mul_f32_e32 v36, v36, v242
	v_mul_f32_e32 v37, v37, v242
	v_mul_f32_e32 v38, v38, v242
	v_mul_f32_e32 v39, v39, v242
.La0_nr_a7_1:
	v_mfma_f32_16x16x32_bf16 v[8:11], v[140:143], v[156:159], v[8:11]
	v_sub_f32_e32 v232, v232, v89
	v_sub_f32_e32 v233, v233, v89
	v_sub_f32_e32 v234, v234, v89
	v_sub_f32_e32 v235, v235, v89
	v_mfma_f32_16x16x32_bf16 v[12:15], v[144:147], v[156:159], v[12:15]
	v_sub_f32_e32 v236, v236, v89
	v_sub_f32_e32 v237, v237, v89
	v_sub_f32_e32 v238, v238, v89
	v_sub_f32_e32 v239, v239, v89
	v_mfma_f32_16x16x32_bf16 v[16:19], v[148:151], v[156:159], v[16:19]
	v_exp_f32_e32 v232, v232
	v_exp_f32_e32 v233, v233
	v_exp_f32_e32 v234, v234
	v_exp_f32_e32 v235, v235
	v_mfma_f32_16x16x32_bf16 v[20:23], v[152:155], v[156:159], v[20:23]
	v_exp_f32_e32 v236, v236
	v_exp_f32_e32 v237, v237
	v_exp_f32_e32 v238, v238
	v_exp_f32_e32 v239, v239
	v_mfma_f32_16x16x32_bf16 v[72:75], v[176:179], v[156:159], v[72:75]
	s_nop 0
	v_cvt_pk_bf16_f32 v232, v232, v233
	v_cvt_pk_bf16_f32 v233, v234, v235
	v_cvt_pk_bf16_f32 v234, v236, v237
	v_cvt_pk_bf16_f32 v235, v238, v239
	v_add_f32_e32 v1, 0x41000000, v90
	v_max3_f32 v3, v180, v181, v182
	v_max3_f32 v4, v183, v184, v185
	v_max3_f32 v3, v3, v186, v187
	v_max_f32_e32 v3, v3, v4
	v_cmp_gt_f32_e32 vcc, v3, v1
	s_cbranch_vccz .La0_nr_a7_2
	ds_bpermute_b32 v4, v194, v3
	s_waitcnt lgkmcnt(0)
	v_max_f32_e32 v3, v3, v4
	ds_bpermute_b32 v4, v195, v3
	s_waitcnt lgkmcnt(0)
	v_max3_f32 v3, v3, v4, v90
	v_sub_f32_e32 v4, v90, v3
	v_exp_f32_e32 v4, v4
	v_mov_b32_e32 v90, v3
	s_nop 0
	v_mul_f32_e32 v80, v80, v4
	v_mul_f32_e32 v81, v81, v4
	v_mul_f32_e32 v82, v82, v4
	v_mul_f32_e32 v83, v83, v4
	v_mul_f32_e32 v40, v40, v4
	v_mul_f32_e32 v41, v41, v4
	v_mul_f32_e32 v42, v42, v4
	v_mul_f32_e32 v43, v43, v4
	v_mul_f32_e32 v44, v44, v4
	v_mul_f32_e32 v45, v45, v4
	v_mul_f32_e32 v46, v46, v4
	v_mul_f32_e32 v47, v47, v4
	v_mul_f32_e32 v48, v48, v4
	v_mul_f32_e32 v49, v49, v4
	v_mul_f32_e32 v50, v50, v4
	v_mul_f32_e32 v51, v51, v4
	v_mul_f32_e32 v52, v52, v4
	v_mul_f32_e32 v53, v53, v4
	v_mul_f32_e32 v54, v54, v4
	v_mul_f32_e32 v55, v55, v4
.La0_nr_a7_2:
	v_mfma_f32_16x16x32_bf16 v[24:27], v[140:143], v[232:235], v[24:27]
	v_sub_f32_e32 v180, v180, v90
	v_sub_f32_e32 v181, v181, v90
	v_sub_f32_e32 v182, v182, v90
	v_sub_f32_e32 v183, v183, v90
	v_mfma_f32_16x16x32_bf16 v[28:31], v[144:147], v[232:235], v[28:31]
	v_sub_f32_e32 v184, v184, v90
	v_sub_f32_e32 v185, v185, v90
	v_sub_f32_e32 v186, v186, v90
	v_sub_f32_e32 v187, v187, v90
	v_mfma_f32_16x16x32_bf16 v[32:35], v[148:151], v[232:235], v[32:35]
	v_exp_f32_e32 v180, v180
	v_exp_f32_e32 v181, v181
	v_exp_f32_e32 v182, v182
	v_exp_f32_e32 v183, v183
	v_mfma_f32_16x16x32_bf16 v[36:39], v[152:155], v[232:235], v[36:39]
	v_exp_f32_e32 v184, v184
	v_exp_f32_e32 v185, v185
	v_exp_f32_e32 v186, v186
	v_exp_f32_e32 v187, v187
	v_mfma_f32_16x16x32_bf16 v[76:79], v[176:179], v[232:235], v[76:79]
	s_nop 0
	v_cvt_pk_bf16_f32 v180, v180, v181
	v_cvt_pk_bf16_f32 v181, v182, v183
	v_cvt_pk_bf16_f32 v182, v184, v185
	v_cvt_pk_bf16_f32 v183, v186, v187
	s_nop 1
	v_mfma_f32_16x16x32_bf16 v[40:43], v[140:143], v[180:183], v[40:43]
	v_mfma_f32_16x16x32_bf16 v[44:47], v[144:147], v[180:183], v[44:47]
	v_mfma_f32_16x16x32_bf16 v[48:51], v[148:151], v[180:183], v[48:51]
	v_mfma_f32_16x16x32_bf16 v[52:55], v[152:155], v[180:183], v[52:55]
	v_mfma_f32_16x16x32_bf16 v[80:83], v[176:179], v[180:183], v[80:83]
	s_branch .La0_rowdone_a
.La0_pa_14:
	ds_read_b128 v[232:235], v167 offset:8192
	ds_read_b128 v[236:239], v167 offset:9216
	ds_read_b128 v[180:183], v167 offset:4096
	ds_read_b128 v[184:187], v167 offset:5120
	ds_read_b128 v[198:201], v167 offset:0
	ds_read_b128 v[202:205], v167 offset:1024
	s_waitcnt lgkmcnt(4)
	v_mfma_f32_16x16x32_bf16 v[232:235], v[124:127], v[100:103], v[232:235]
	v_mfma_f32_16x16x32_bf16 v[236:239], v[132:135], v[100:103], v[236:239]
	v_mfma_f32_16x16x32_bf16 v[232:235], v[128:131], v[104:107], v[232:235]
	v_mfma_f32_16x16x32_bf16 v[236:239], v[136:139], v[104:107], v[236:239]
	s_waitcnt lgkmcnt(2)
	v_mfma_f32_16x16x32_bf16 v[180:183], v[124:127], v[108:111], v[180:183]
	v_mfma_f32_16x16x32_bf16 v[184:187], v[132:135], v[108:111], v[184:187]
	v_mfma_f32_16x16x32_bf16 v[180:183], v[128:131], v[112:115], v[180:183]
	v_mfma_f32_16x16x32_bf16 v[184:187], v[136:139], v[112:115], v[184:187]
	v_add_f32_e32 v240, 0x41000000, v89
	s_nop 3
	v_max3_f32 v241, v232, v233, v234
	v_max3_f32 v242, v235, v236, v237
	v_max3_f32 v241, v241, v238, v239
	v_max_f32_e32 v241, v241, v242
	v_cmp_gt_f32_e32 vcc, v241, v240
	s_cbranch_vccz .La0_nr_a14_1
	ds_bpermute_b32 v242, v194, v241
	s_waitcnt lgkmcnt(0)
	v_max_f32_e32 v241, v241, v242
	ds_bpermute_b32 v242, v195, v241
	s_waitcnt lgkmcnt(0)
	v_max3_f32 v241, v241, v242, v89
	v_sub_f32_e32 v242, v89, v241
	v_exp_f32_e32 v242, v242
	v_mov_b32_e32 v89, v241
	s_nop 0
	v_mul_f32_e32 v76, v76, v242
	v_mul_f32_e32 v77, v77, v242
	v_mul_f32_e32 v78, v78, v242
	v_mul_f32_e32 v79, v79, v242
	v_mul_f32_e32 v24, v24, v242
	v_mul_f32_e32 v25, v25, v242
	v_mul_f32_e32 v26, v26, v242
	v_mul_f32_e32 v27, v27, v242
	v_mul_f32_e32 v28, v28, v242
	v_mul_f32_e32 v29, v29, v242
	v_mul_f32_e32 v30, v30, v242
	v_mul_f32_e32 v31, v31, v242
	v_mul_f32_e32 v32, v32, v242
	v_mul_f32_e32 v33, v33, v242
	v_mul_f32_e32 v34, v34, v242
	v_mul_f32_e32 v35, v35, v242
	v_mul_f32_e32 v36, v36, v242
	v_mul_f32_e32 v37, v37, v242
	v_mul_f32_e32 v38, v38, v242
	v_mul_f32_e32 v39, v39, v242
.La0_nr_a14_1:
	v_sub_f32_e32 v232, v232, v89
	v_sub_f32_e32 v233, v233, v89
	v_sub_f32_e32 v234, v234, v89
	v_sub_f32_e32 v235, v235, v89
	v_sub_f32_e32 v236, v236, v89
	v_sub_f32_e32 v237, v237, v89
	v_sub_f32_e32 v238, v238, v89
	v_sub_f32_e32 v239, v239, v89
	v_exp_f32_e32 v232, v232
	v_exp_f32_e32 v233, v233
	v_exp_f32_e32 v234, v234
	v_exp_f32_e32 v235, v235
	v_exp_f32_e32 v236, v236
	v_exp_f32_e32 v237, v237
	v_exp_f32_e32 v238, v238
	v_exp_f32_e32 v239, v239
	s_nop 0
	v_cvt_pk_bf16_f32 v232, v232, v233
	v_cvt_pk_bf16_f32 v233, v234, v235
	v_cvt_pk_bf16_f32 v234, v236, v237
	v_cvt_pk_bf16_f32 v235, v238, v239
	s_waitcnt lgkmcnt(0)
	v_mfma_f32_16x16x32_bf16 v[198:201], v[124:127], v[116:119], v[198:201]
	v_add_f32_e32 v1, 0x41000000, v90
	v_max3_f32 v3, v180, v181, v182
	v_mfma_f32_16x16x32_bf16 v[202:205], v[132:135], v[116:119], v[202:205]
	v_max3_f32 v4, v183, v184, v185
	v_max3_f32 v3, v3, v186, v187
	v_mfma_f32_16x16x32_bf16 v[198:201], v[128:131], v[120:123], v[198:201]
	v_max_f32_e32 v3, v3, v4
	v_cmp_gt_f32_e32 vcc, v3, v1
	v_mfma_f32_16x16x32_bf16 v[202:205], v[136:139], v[120:123], v[202:205]
	s_cbranch_vccz .La0_nr_a14_2
	ds_bpermute_b32 v4, v194, v3
	s_waitcnt lgkmcnt(0)
	v_max_f32_e32 v3, v3, v4
	ds_bpermute_b32 v4, v195, v3
	s_waitcnt lgkmcnt(0)
	v_max3_f32 v3, v3, v4, v90
	v_sub_f32_e32 v4, v90, v3
	v_exp_f32_e32 v4, v4
	v_mov_b32_e32 v90, v3
	s_nop 0
	v_mul_f32_e32 v80, v80, v4
	v_mul_f32_e32 v81, v81, v4
	v_mul_f32_e32 v82, v82, v4
	v_mul_f32_e32 v83, v83, v4
	v_mul_f32_e32 v40, v40, v4
	v_mul_f32_e32 v41, v41, v4
	v_mul_f32_e32 v42, v42, v4
	v_mul_f32_e32 v43, v43, v4
	v_mul_f32_e32 v44, v44, v4
	v_mul_f32_e32 v45, v45, v4
	v_mul_f32_e32 v46, v46, v4
	v_mul_f32_e32 v47, v47, v4
	v_mul_f32_e32 v48, v48, v4
	v_mul_f32_e32 v49, v49, v4
	v_mul_f32_e32 v50, v50, v4
	v_mul_f32_e32 v51, v51, v4
	v_mul_f32_e32 v52, v52, v4
	v_mul_f32_e32 v53, v53, v4
	v_mul_f32_e32 v54, v54, v4
	v_mul_f32_e32 v55, v55, v4

.La0_pa_3:
	ds_read_b128 v[156:159], v167 offset:12288
	ds_read_b128 v[160:163], v167 offset:13312
	ds_read_b128 v[232:235], v167 offset:8192
	ds_read_b128 v[236:239], v167 offset:9216
	s_waitcnt lgkmcnt(2)
	v_mfma_f32_16x16x32_bf16 v[156:159], v[124:127], v[92:95], v[156:159]
	v_mfma_f32_16x16x32_bf16 v[160:163], v[132:135], v[92:95], v[160:163]
	v_mfma_f32_16x16x32_bf16 v[156:159], v[128:131], v[96:99], v[156:159]
	v_mfma_f32_16x16x32_bf16 v[160:163], v[136:139], v[96:99], v[160:163]
	s_waitcnt lgkmcnt(0)
	v_mfma_f32_16x16x32_bf16 v[232:235], v[124:127], v[100:103], v[232:235]
	v_mfma_f32_16x16x32_bf16 v[236:239], v[132:135], v[100:103], v[236:239]
	v_mfma_f32_16x16x32_bf16 v[232:235], v[128:131], v[104:107], v[232:235]
	v_mfma_f32_16x16x32_bf16 v[236:239], v[136:139], v[104:107], v[236:239]
	v_add_f32_e32 v164, 0x41000000, v88
	s_nop 3
	v_max3_f32 v165, v156, v157, v158
	v_max3_f32 v166, v159, v160, v161
	v_max3_f32 v165, v165, v162, v163
	v_max_f32_e32 v165, v165, v166
	v_cmp_gt_f32_e32 vcc, v165, v164
	s_cbranch_vccz .La0_nr_a3_0
	ds_bpermute_b32 v166, v194, v165
	s_waitcnt lgkmcnt(0)
	v_max_f32_e32 v165, v165, v166
	ds_bpermute_b32 v166, v195, v165
	s_waitcnt lgkmcnt(0)
	v_max3_f32 v165, v165, v166, v88
	v_sub_f32_e32 v166, v88, v165
	v_exp_f32_e32 v166, v166
	v_mov_b32_e32 v88, v165
	s_nop 0
	v_mul_f32_e32 v72, v72, v166
	v_mul_f32_e32 v73, v73, v166
	v_mul_f32_e32 v74, v74, v166
	v_mul_f32_e32 v75, v75, v166
	v_mul_f32_e32 v8, v8, v166
	v_mul_f32_e32 v9, v9, v166
	v_mul_f32_e32 v10, v10, v166
	v_mul_f32_e32 v11, v11, v166
	v_mul_f32_e32 v12, v12, v166
	v_mul_f32_e32 v13, v13, v166
	v_mul_f32_e32 v14, v14, v166
	v_mul_f32_e32 v15, v15, v166
	v_mul_f32_e32 v16, v16, v166
	v_mul_f32_e32 v17, v17, v166
	v_mul_f32_e32 v18, v18, v166
	v_mul_f32_e32 v19, v19, v166
	v_mul_f32_e32 v20, v20, v166
	v_mul_f32_e32 v21, v21, v166
	v_mul_f32_e32 v22, v22, v166
	v_mul_f32_e32 v23, v23, v166
.La0_nr_a3_0:
	v_sub_f32_e32 v156, v156, v88
	v_sub_f32_e32 v157, v157, v88
	v_sub_f32_e32 v158, v158, v88
	v_sub_f32_e32 v159, v159, v88
	v_sub_f32_e32 v160, v160, v88
	v_sub_f32_e32 v161, v161, v88
	v_sub_f32_e32 v162, v162, v88
	v_sub_f32_e32 v163, v163, v88
	v_exp_f32_e32 v156, v156
	v_exp_f32_e32 v157, v157
	v_exp_f32_e32 v158, v158
	v_exp_f32_e32 v159, v159
	v_exp_f32_e32 v160, v160
	v_exp_f32_e32 v161, v161
	v_exp_f32_e32 v162, v162
	v_exp_f32_e32 v163, v163
	s_nop 0
	v_cvt_pk_bf16_f32 v156, v156, v157
	v_cvt_pk_bf16_f32 v157, v158, v159
	v_cvt_pk_bf16_f32 v158, v160, v161
	v_cvt_pk_bf16_f32 v159, v162, v163
	v_add_f32_e32 v240, 0x41000000, v89
	v_max3_f32 v241, v232, v233, v234
	v_max3_f32 v242, v235, v236, v237
	v_max3_f32 v241, v241, v238, v239
	v_max_f32_e32 v241, v241, v242
	v_cmp_gt_f32_e32 vcc, v241, v240
	s_cbranch_vccz .La0_nr_a3_1
	ds_bpermute_b32 v242, v194, v241
	s_waitcnt lgkmcnt(0)
	v_max_f32_e32 v241, v241, v242
	ds_bpermute_b32 v242, v195, v241
	s_waitcnt lgkmcnt(0)
	v_max3_f32 v241, v241, v242, v89
	v_sub_f32_e32 v242, v89, v241
	v_exp_f32_e32 v242, v242
	v_mov_b32_e32 v89, v241
	s_nop 0
	v_mul_f32_e32 v76, v76, v242
	v_mul_f32_e32 v77, v77, v242
	v_mul_f32_e32 v78, v78, v242
	v_mul_f32_e32 v79, v79, v242
	v_mul_f32_e32 v24, v24, v242
	v_mul_f32_e32 v25, v25, v242
	v_mul_f32_e32 v26, v26, v242
	v_mul_f32_e32 v27, v27, v242
	v_mul_f32_e32 v28, v28, v242
	v_mul_f32_e32 v29, v29, v242
	v_mul_f32_e32 v30, v30, v242
	v_mul_f32_e32 v31, v31, v242
	v_mul_f32_e32 v32, v32, v242
	v_mul_f32_e32 v33, v33, v242
	v_mul_f32_e32 v34, v34, v242
	v_mul_f32_e32 v35, v35, v242
	v_mul_f32_e32 v36, v36, v242
	v_mul_f32_e32 v37, v37, v242
	v_mul_f32_e32 v38, v38, v242
	v_mul_f32_e32 v39, v39, v242
.La0_nr_a3_1:
	v_mfma_f32_16x16x32_bf16 v[8:11], v[140:143], v[156:159], v[8:11]
	v_sub_f32_e32 v232, v232, v89
	v_sub_f32_e32 v233, v233, v89
	v_sub_f32_e32 v234, v234, v89
	v_sub_f32_e32 v235, v235, v89
	v_mfma_f32_16x16x32_bf16 v[12:15], v[144:147], v[156:159], v[12:15]
	v_sub_f32_e32 v236, v236, v89
	v_sub_f32_e32 v237, v237, v89
	v_sub_f32_e32 v238, v238, v89
	v_sub_f32_e32 v239, v239, v89
	v_mfma_f32_16x16x32_bf16 v[16:19], v[148:151], v[156:159], v[16:19]
	v_exp_f32_e32 v232, v232
	v_exp_f32_e32 v233, v233
	v_exp_f32_e32 v234, v234
	v_exp_f32_e32 v235, v235
	v_mfma_f32_16x16x32_bf16 v[20:23], v[152:155], v[156:159], v[20:23]
	v_exp_f32_e32 v236, v236
	v_exp_f32_e32 v237, v237
	v_exp_f32_e32 v238, v238
	v_exp_f32_e32 v239, v239
	v_mfma_f32_16x16x32_bf16 v[72:75], v[176:179], v[156:159], v[72:75]
	s_nop 0
	v_cvt_pk_bf16_f32 v232, v232, v233
	v_cvt_pk_bf16_f32 v233, v234, v235
	v_cvt_pk_bf16_f32 v234, v236, v237
	v_cvt_pk_bf16_f32 v235, v238, v239
	s_nop 1
	v_mfma_f32_16x16x32_bf16 v[24:27], v[140:143], v[232:235], v[24:27]
	v_mfma_f32_16x16x32_bf16 v[28:31], v[144:147], v[232:235], v[28:31]
	v_mfma_f32_16x16x32_bf16 v[32:35], v[148:151], v[232:235], v[32:35]
	v_mfma_f32_16x16x32_bf16 v[36:39], v[152:155], v[232:235], v[36:39]
	v_mfma_f32_16x16x32_bf16 v[76:79], v[176:179], v[232:235], v[76:79]
	s_branch .La0_rowdone_a
.La0_pa_12:
	ds_read_b128 v[180:183], v167 offset:4096
	ds_read_b128 v[184:187], v167 offset:5120
	ds_read_b128 v[198:201], v167 offset:0
	ds_read_b128 v[202:205], v167 offset:1024
	s_waitcnt lgkmcnt(2)
	v_mfma_f32_16x16x32_bf16 v[180:183], v[124:127], v[108:111], v[180:183]
	v_mfma_f32_16x16x32_bf16 v[184:187], v[132:135], v[108:111], v[184:187]
	v_mfma_f32_16x16x32_bf16 v[180:183], v[128:131], v[112:115], v[180:183]
	v_mfma_f32_16x16x32_bf16 v[184:187], v[136:139], v[112:115], v[184:187]
	s_waitcnt lgkmcnt(0)
	v_mfma_f32_16x16x32_bf16 v[198:201], v[124:127], v[116:119], v[198:201]
	v_mfma_f32_16x16x32_bf16 v[202:205], v[132:135], v[116:119], v[202:205]
	v_mfma_f32_16x16x32_bf16 v[198:201], v[128:131], v[120:123], v[198:201]
	v_mfma_f32_16x16x32_bf16 v[202:205], v[136:139], v[120:123], v[202:205]
	v_add_f32_e32 v1, 0x41000000, v90
	s_nop 3
	v_max3_f32 v3, v180, v181, v182
	v_max3_f32 v4, v183, v184, v185
	v_max3_f32 v3, v3, v186, v187
	v_max_f32_e32 v3, v3, v4
	v_cmp_gt_f32_e32 vcc, v3, v1
	s_cbranch_vccz .La0_nr_a12_2
	ds_bpermute_b32 v4, v194, v3
	s_waitcnt lgkmcnt(0)
	v_max_f32_e32 v3, v3, v4
	ds_bpermute_b32 v4, v195, v3
	s_waitcnt lgkmcnt(0)
	v_max3_f32 v3, v3, v4, v90
	v_sub_f32_e32 v4, v90, v3
	v_exp_f32_e32 v4, v4
	v_mov_b32_e32 v90, v3
	s_nop 0
	v_mul_f32_e32 v80, v80, v4
	v_mul_f32_e32 v81, v81, v4
	v_mul_f32_e32 v82, v82, v4
	v_mul_f32_e32 v83, v83, v4
	v_mul_f32_e32 v40, v40, v4
	v_mul_f32_e32 v41, v41, v4
	v_mul_f32_e32 v42, v42, v4
	v_mul_f32_e32 v43, v43, v4
	v_mul_f32_e32 v44, v44, v4
	v_mul_f32_e32 v45, v45, v4
	v_mul_f32_e32 v46, v46, v4
	v_mul_f32_e32 v47, v47, v4
	v_mul_f32_e32 v48, v48, v4
	v_mul_f32_e32 v49, v49, v4
	v_mul_f32_e32 v50, v50, v4
	v_mul_f32_e32 v51, v51, v4
	v_mul_f32_e32 v52, v52, v4
	v_mul_f32_e32 v53, v53, v4
	v_mul_f32_e32 v54, v54, v4
	v_mul_f32_e32 v55, v55, v4
.La0_nr_a12_2:
	v_sub_f32_e32 v180, v180, v90
	v_sub_f32_e32 v181, v181, v90
	v_sub_f32_e32 v182, v182, v90
	v_sub_f32_e32 v183, v183, v90
	v_sub_f32_e32 v184, v184, v90
	v_sub_f32_e32 v185, v185, v90
	v_sub_f32_e32 v186, v186, v90
	v_sub_f32_e32 v187, v187, v90
	v_exp_f32_e32 v180, v180
	v_exp_f32_e32 v181, v181
	v_exp_f32_e32 v182, v182
	v_exp_f32_e32 v183, v183
	v_exp_f32_e32 v184, v184
	v_exp_f32_e32 v185, v185
	v_exp_f32_e32 v186, v186
	v_exp_f32_e32 v187, v187
	s_nop 0
	v_cvt_pk_bf16_f32 v180, v180, v181
	v_cvt_pk_bf16_f32 v181, v182, v183
	v_cvt_pk_bf16_f32 v182, v184, v185
	v_cvt_pk_bf16_f32 v183, v186, v187
	v_add_f32_e32 v5, 0x41000000, v91
	v_max3_f32 v7, v198, v199, v200
	v_max3_f32 v206, v201, v202, v203
	v_max3_f32 v7, v7, v204, v205
	v_max_f32_e32 v7, v7, v206
	v_cmp_gt_f32_e32 vcc, v7, v5
	s_cbranch_vccz .La0_nr_a12_3
	ds_bpermute_b32 v206, v194, v7
	s_waitcnt lgkmcnt(0)
	v_max_f32_e32 v7, v7, v206
	ds_bpermute_b32 v206, v195, v7
	s_waitcnt lgkmcnt(0)
	v_max3_f32 v7, v7, v206, v91
	v_sub_f32_e32 v206, v91, v7
	v_exp_f32_e32 v206, v206
	v_mov_b32_e32 v91, v7
	s_nop 0
	v_mul_f32_e32 v84, v84, v206
	v_mul_f32_e32 v85, v85, v206
	v_mul_f32_e32 v86, v86, v206
	v_mul_f32_e32 v87, v87, v206
	v_mul_f32_e32 v56, v56, v206
	v_mul_f32_e32 v57, v57, v206
	v_mul_f32_e32 v58, v58, v206
	v_mul_f32_e32 v59, v59, v206
	v_mul_f32_e32 v60, v60, v206
	v_mul_f32_e32 v61, v61, v206
	v_mul_f32_e32 v62, v62, v206
	v_mul_f32_e32 v63, v63, v206
	v_mul_f32_e32 v64, v64, v206
	v_mul_f32_e32 v65, v65, v206
	v_mul_f32_e32 v66, v66, v206
	v_mul_f32_e32 v67, v67, v206
	v_mul_f32_e32 v68, v68, v206
	v_mul_f32_e32 v69, v69, v206
	v_mul_f32_e32 v70, v70, v206
	v_mul_f32_e32 v71, v71, v206

.La0_pa_1:
	ds_read_b128 v[156:159], v167 offset:12288
	ds_read_b128 v[160:163], v167 offset:13312
	s_waitcnt lgkmcnt(0)
	v_mfma_f32_16x16x32_bf16 v[156:159], v[124:127], v[92:95], v[156:159]
	v_mfma_f32_16x16x32_bf16 v[160:163], v[132:135], v[92:95], v[160:163]
	v_mfma_f32_16x16x32_bf16 v[156:159], v[128:131], v[96:99], v[156:159]
	v_mfma_f32_16x16x32_bf16 v[160:163], v[136:139], v[96:99], v[160:163]
	v_add_f32_e32 v164, 0x41000000, v88
	s_nop 7
	v_max3_f32 v165, v156, v157, v158
	v_max3_f32 v166, v159, v160, v161
	v_max3_f32 v165, v165, v162, v163
	v_max_f32_e32 v165, v165, v166
	v_cmp_gt_f32_e32 vcc, v165, v164
	s_cbranch_vccz .La0_nr_a1_0
	ds_bpermute_b32 v166, v194, v165
	s_waitcnt lgkmcnt(0)
	v_max_f32_e32 v165, v165, v166
	ds_bpermute_b32 v166, v195, v165
	s_waitcnt lgkmcnt(0)
	v_max3_f32 v165, v165, v166, v88
	v_sub_f32_e32 v166, v88, v165
	v_exp_f32_e32 v166, v166
	v_mov_b32_e32 v88, v165
	s_nop 0
	v_mul_f32_e32 v72, v72, v166
	v_mul_f32_e32 v73, v73, v166
	v_mul_f32_e32 v74, v74, v166
	v_mul_f32_e32 v75, v75, v166
	v_mul_f32_e32 v8, v8, v166
	v_mul_f32_e32 v9, v9, v166
	v_mul_f32_e32 v10, v10, v166
	v_mul_f32_e32 v11, v11, v166
	v_mul_f32_e32 v12, v12, v166
	v_mul_f32_e32 v13, v13, v166
	v_mul_f32_e32 v14, v14, v166
	v_mul_f32_e32 v15, v15, v166
	v_mul_f32_e32 v16, v16, v166
	v_mul_f32_e32 v17, v17, v166
	v_mul_f32_e32 v18, v18, v166
	v_mul_f32_e32 v19, v19, v166
	v_mul_f32_e32 v20, v20, v166
	v_mul_f32_e32 v21, v21, v166
	v_mul_f32_e32 v22, v22, v166
	v_mul_f32_e32 v23, v23, v166
.La0_nr_a1_0:
	v_sub_f32_e32 v156, v156, v88
	v_sub_f32_e32 v157, v157, v88
	v_sub_f32_e32 v158, v158, v88
	v_sub_f32_e32 v159, v159, v88
	v_sub_f32_e32 v160, v160, v88
	v_sub_f32_e32 v161, v161, v88
	v_sub_f32_e32 v162, v162, v88
	v_sub_f32_e32 v163, v163, v88
	v_exp_f32_e32 v156, v156
	v_exp_f32_e32 v157, v157
	v_exp_f32_e32 v158, v158
	v_exp_f32_e32 v159, v159
	v_exp_f32_e32 v160, v160
	v_exp_f32_e32 v161, v161
	v_exp_f32_e32 v162, v162
	v_exp_f32_e32 v163, v163
	s_nop 0
	v_cvt_pk_bf16_f32 v156, v156, v157
	v_cvt_pk_bf16_f32 v157, v158, v159
	v_cvt_pk_bf16_f32 v158, v160, v161
	v_cvt_pk_bf16_f32 v159, v162, v163
	s_nop 1
	v_mfma_f32_16x16x32_bf16 v[8:11], v[140:143], v[156:159], v[8:11]
	v_mfma_f32_16x16x32_bf16 v[12:15], v[144:147], v[156:159], v[12:15]
	v_mfma_f32_16x16x32_bf16 v[16:19], v[148:151], v[156:159], v[16:19]
	v_mfma_f32_16x16x32_bf16 v[20:23], v[152:155], v[156:159], v[20:23]
	v_mfma_f32_16x16x32_bf16 v[72:75], v[176:179], v[156:159], v[72:75]
	s_branch .La0_rowdone_a
.La0_pa_8:
	ds_read_b128 v[198:201], v167 offset:0
	ds_read_b128 v[202:205], v167 offset:1024
	s_waitcnt lgkmcnt(0)
	v_mfma_f32_16x16x32_bf16 v[198:201], v[124:127], v[116:119], v[198:201]
	v_mfma_f32_16x16x32_bf16 v[202:205], v[132:135], v[116:119], v[202:205]
	v_mfma_f32_16x16x32_bf16 v[198:201], v[128:131], v[120:123], v[198:201]
	v_mfma_f32_16x16x32_bf16 v[202:205], v[136:139], v[120:123], v[202:205]
	v_add_f32_e32 v5, 0x41000000, v91
	s_nop 7
	v_max3_f32 v7, v198, v199, v200
	v_max3_f32 v206, v201, v202, v203
	v_max3_f32 v7, v7, v204, v205
	v_max_f32_e32 v7, v7, v206
	v_cmp_gt_f32_e32 vcc, v7, v5
	s_cbranch_vccz .La0_nr_a8_3
	ds_bpermute_b32 v206, v194, v7
	s_waitcnt lgkmcnt(0)
	v_max_f32_e32 v7, v7, v206
	ds_bpermute_b32 v206, v195, v7
	s_waitcnt lgkmcnt(0)
	v_max3_f32 v7, v7, v206, v91
	v_sub_f32_e32 v206, v91, v7
	v_exp_f32_e32 v206, v206
	v_mov_b32_e32 v91, v7
	s_nop 0
	v_mul_f32_e32 v84, v84, v206
	v_mul_f32_e32 v85, v85, v206
	v_mul_f32_e32 v86, v86, v206
	v_mul_f32_e32 v87, v87, v206
	v_mul_f32_e32 v56, v56, v206
	v_mul_f32_e32 v57, v57, v206
	v_mul_f32_e32 v58, v58, v206
	v_mul_f32_e32 v59, v59, v206
	v_mul_f32_e32 v60, v60, v206
	v_mul_f32_e32 v61, v61, v206
	v_mul_f32_e32 v62, v62, v206
	v_mul_f32_e32 v63, v63, v206
	v_mul_f32_e32 v64, v64, v206
	v_mul_f32_e32 v65, v65, v206
	v_mul_f32_e32 v66, v66, v206
	v_mul_f32_e32 v67, v67, v206
	v_mul_f32_e32 v68, v68, v206
	v_mul_f32_e32 v69, v69, v206
	v_mul_f32_e32 v70, v70, v206
	v_mul_f32_e32 v71, v71, v206
.La0_nr_a8_3:
	v_sub_f32_e32 v198, v198, v91
	v_sub_f32_e32 v199, v199, v91
	v_sub_f32_e32 v200, v200, v91
	v_sub_f32_e32 v201, v201, v91
	v_sub_f32_e32 v202, v202, v91
	v_sub_f32_e32 v203, v203, v91
	v_sub_f32_e32 v204, v204, v91
	v_sub_f32_e32 v205, v205, v91
	v_exp_f32_e32 v198, v198
	v_exp_f32_e32 v199, v199
	v_exp_f32_e32 v200, v200
	v_exp_f32_e32 v201, v201
	v_exp_f32_e32 v202, v202
	v_exp_f32_e32 v203, v203
	v_exp_f32_e32 v204, v204
	v_exp_f32_e32 v205, v205
	s_nop 0
	v_cvt_pk_bf16_f32 v198, v198, v199
	v_cvt_pk_bf16_f32 v199, v200, v201
	v_cvt_pk_bf16_f32 v200, v202, v203
	v_cvt_pk_bf16_f32 v201, v204, v205
	s_nop 1
	v_mfma_f32_16x16x32_bf16 v[56:59], v[140:143], v[198:201], v[56:59]
	v_mfma_f32_16x16x32_bf16 v[60:63], v[144:147], v[198:201], v[60:63]
	v_mfma_f32_16x16x32_bf16 v[64:67], v[148:151], v[198:201], v[64:67]
	v_mfma_f32_16x16x32_bf16 v[68:71], v[152:155], v[198:201], v[68:71]
	v_mfma_f32_16x16x32_bf16 v[84:87], v[176:179], v[198:201], v[84:87]
	s_branch .La0_rowdone_a

.La0_gateld:
	s_add_i32 s5, s41, s54
	s_add_i32 s5, s5, 0
	s_lshl_b32 s5, s5, 17
	s_add_u32 s0, s56, s5
	s_addc_u32 s1, s57, 0
	global_load_dwordx4 v[210:213], v196, s[0:1] nt
	global_load_dwordx4 v[214:217], v196, s[0:1] offset:16 nt
	s_add_i32 s5, s41, s54
	s_add_i32 s5, s5, 2
	s_lshl_b32 s5, s5, 17
	s_add_u32 s0, s56, s5
	s_addc_u32 s1, s57, 0
	global_load_dwordx4 v[218:221], v196, s[0:1] nt
	global_load_dwordx4 v[222:225], v196, s[0:1] offset:16 nt
	s_add_i32 s5, s41, s54
	s_add_i32 s5, s5, 4
	s_lshl_b32 s5, s5, 17
	s_add_u32 s0, s56, s5
	s_addc_u32 s1, s57, 0
	global_load_dwordx4 v[124:127], v196, s[0:1] nt
	global_load_dwordx4 v[128:131], v196, s[0:1] offset:16 nt
	s_add_i32 s5, s41, s54
	s_add_i32 s5, s5, 6
	s_lshl_b32 s5, s5, 17
	s_add_u32 s0, s56, s5
	s_addc_u32 s1, s57, 0
	global_load_dwordx4 v[132:135], v196, s[0:1] nt
	global_load_dwordx4 v[136:139], v196, s[0:1] offset:16 nt
.La0_issued:
	s_cmp_eq_u32 s32, 0
	s_cbranch_scc1 .La0_ss_done
	s_and_b32 s61, s62, 1
	s_lshl_b32 s61, s61, 15
	s_add_i32 s0, s61, 0x4000
	v_add_u32_e32 v209, s0, v190
	ds_read_b128 v[140:143], v209 offset:0
	ds_read_b128 v[144:147], v209 offset:512
	ds_read_b128 v[148:151], v209 offset:1024
	ds_read_b128 v[152:155], v209 offset:1536
	s_add_i32 s60, s60, 1
	s_sub_i32 s0, s60, s41
	s_sub_i32 s0, s0, s54
	s_add_i32 s0, s0, 1
	s_lshl_b32 s0, s0, 11
	v_add_u32_e32 v167, s0, v250
	s_cmp_eq_u32 s32, 15
	s_cbranch_scc1 .La0_pb_15
	s_cmp_eq_u32 s32, 7
	s_cbranch_scc1 .La0_pb_7
	s_cmp_eq_u32 s32, 14
	s_cbranch_scc1 .La0_pb_14
	s_cmp_eq_u32 s32, 3
	s_cbranch_scc1 .La0_pb_3
	s_cmp_eq_u32 s32, 12
	s_cbranch_scc1 .La0_pb_12
	s_cmp_eq_u32 s32, 1
	s_cbranch_scc1 .La0_pb_1
	s_cmp_eq_u32 s32, 8
	s_cbranch_scc1 .La0_pb_8
	s_branch .La0_rowdone_b
.La0_pb_15:
	ds_read_b128 v[156:159], v167 offset:12288
	ds_read_b128 v[160:163], v167 offset:13312
	ds_read_b128 v[232:235], v167 offset:8192
	ds_read_b128 v[236:239], v167 offset:9216
	ds_read_b128 v[180:183], v167 offset:4096
	ds_read_b128 v[184:187], v167 offset:5120
	ds_read_b128 v[198:201], v167 offset:0
	ds_read_b128 v[202:205], v167 offset:1024
	s_waitcnt lgkmcnt(6)
	v_mfma_f32_16x16x32_bf16 v[156:159], v[168:171], v[92:95], v[156:159]
	v_mfma_f32_16x16x32_bf16 v[160:163], v[226:229], v[92:95], v[160:163]
	v_mfma_f32_16x16x32_bf16 v[156:159], v[172:175], v[96:99], v[156:159]
	v_mfma_f32_16x16x32_bf16 v[160:163], v[244:247], v[96:99], v[160:163]
	s_waitcnt lgkmcnt(4)
	v_mfma_f32_16x16x32_bf16 v[232:235], v[168:171], v[100:103], v[232:235]
	v_mfma_f32_16x16x32_bf16 v[236:239], v[226:229], v[100:103], v[236:239]
	v_mfma_f32_16x16x32_bf16 v[232:235], v[172:175], v[104:107], v[232:235]
	v_mfma_f32_16x16x32_bf16 v[236:239], v[244:247], v[104:107], v[236:239]
	v_add_f32_e32 v164, 0x41000000, v88
	s_nop 3
	v_max3_f32 v165, v156, v157, v158
	v_max3_f32 v166, v159, v160, v161
	v_max3_f32 v165, v165, v162, v163
	v_max_f32_e32 v165, v165, v166
	v_cmp_gt_f32_e32 vcc, v165, v164
	s_cbranch_vccz .La0_nr_b15_0
	ds_bpermute_b32 v166, v194, v165
	s_waitcnt lgkmcnt(0)
	v_max_f32_e32 v165, v165, v166
	ds_bpermute_b32 v166, v195, v165
	s_waitcnt lgkmcnt(0)
	v_max3_f32 v165, v165, v166, v88
	v_sub_f32_e32 v166, v88, v165
	v_exp_f32_e32 v166, v166
	v_mov_b32_e32 v88, v165
	s_nop 0
	v_mul_f32_e32 v72, v72, v166
	v_mul_f32_e32 v73, v73, v166
	v_mul_f32_e32 v74, v74, v166
	v_mul_f32_e32 v75, v75, v166
	v_mul_f32_e32 v8, v8, v166
	v_mul_f32_e32 v9, v9, v166
	v_mul_f32_e32 v10, v10, v166
	v_mul_f32_e32 v11, v11, v166
	v_mul_f32_e32 v12, v12, v166
	v_mul_f32_e32 v13, v13, v166
	v_mul_f32_e32 v14, v14, v166
	v_mul_f32_e32 v15, v15, v166
	v_mul_f32_e32 v16, v16, v166
	v_mul_f32_e32 v17, v17, v166
	v_mul_f32_e32 v18, v18, v166
	v_mul_f32_e32 v19, v19, v166
	v_mul_f32_e32 v20, v20, v166
	v_mul_f32_e32 v21, v21, v166
	v_mul_f32_e32 v22, v22, v166
	v_mul_f32_e32 v23, v23, v166
.La0_nr_b15_0:
	v_sub_f32_e32 v156, v156, v88
	v_sub_f32_e32 v157, v157, v88
	v_sub_f32_e32 v158, v158, v88
	v_sub_f32_e32 v159, v159, v88
	v_sub_f32_e32 v160, v160, v88
	v_sub_f32_e32 v161, v161, v88
	v_sub_f32_e32 v162, v162, v88
	v_sub_f32_e32 v163, v163, v88
	v_exp_f32_e32 v156, v156
	v_exp_f32_e32 v157, v157
	v_exp_f32_e32 v158, v158
	v_exp_f32_e32 v159, v159
	v_exp_f32_e32 v160, v160
	v_exp_f32_e32 v161, v161
	v_exp_f32_e32 v162, v162
	v_exp_f32_e32 v163, v163
	s_nop 0
	v_cvt_pk_bf16_f32 v156, v156, v157
	v_cvt_pk_bf16_f32 v157, v158, v159
	v_cvt_pk_bf16_f32 v158, v160, v161
	v_cvt_pk_bf16_f32 v159, v162, v163
	s_waitcnt lgkmcnt(2)
	v_mfma_f32_16x16x32_bf16 v[180:183], v[168:171], v[108:111], v[180:183]
	v_add_f32_e32 v240, 0x41000000, v89
	v_max3_f32 v241, v232, v233, v234
	v_mfma_f32_16x16x32_bf16 v[184:187], v[226:229], v[108:111], v[184:187]
	v_max3_f32 v242, v235, v236, v237
	v_max3_f32 v241, v241, v238, v239
	v_mfma_f32_16x16x32_bf16 v[180:183], v[172:175], v[112:115], v[180:183]
	v_max_f32_e32 v241, v241, v242
	v_cmp_gt_f32_e32 vcc, v241, v240
	v_mfma_f32_16x16x32_bf16 v[184:187], v[244:247], v[112:115], v[184:187]
	s_cbranch_vccz .La0_nr_b15_1
	ds_bpermute_b32 v242, v194, v241
	s_waitcnt lgkmcnt(0)
	v_max_f32_e32 v241, v241, v242
	ds_bpermute_b32 v242, v195, v241
	s_waitcnt lgkmcnt(0)
	v_max3_f32 v241, v241, v242, v89
	v_sub_f32_e32 v242, v89, v241
	v_exp_f32_e32 v242, v242
	v_mov_b32_e32 v89, v241
	s_nop 0
	v_mul_f32_e32 v76, v76, v242
	v_mul_f32_e32 v77, v77, v242
	v_mul_f32_e32 v78, v78, v242
	v_mul_f32_e32 v79, v79, v242
	v_mul_f32_e32 v24, v24, v242
	v_mul_f32_e32 v25, v25, v242
	v_mul_f32_e32 v26, v26, v242
	v_mul_f32_e32 v27, v27, v242
	v_mul_f32_e32 v28, v28, v242
	v_mul_f32_e32 v29, v29, v242
	v_mul_f32_e32 v30, v30, v242
	v_mul_f32_e32 v31, v31, v242
	v_mul_f32_e32 v32, v32, v242
	v_mul_f32_e32 v33, v33, v242
	v_mul_f32_e32 v34, v34, v242
	v_mul_f32_e32 v35, v35, v242
	v_mul_f32_e32 v36, v36, v242
	v_mul_f32_e32 v37, v37, v242
	v_mul_f32_e32 v38, v38, v242
	v_mul_f32_e32 v39, v39, v242
.La0_nr_b15_1:
	v_mfma_f32_16x16x32_bf16 v[8:11], v[140:143], v[156:159], v[8:11]
	v_sub_f32_e32 v232, v232, v89
	v_sub_f32_e32 v233, v233, v89
	v_sub_f32_e32 v234, v234, v89
	v_sub_f32_e32 v235, v235, v89
	v_mfma_f32_16x16x32_bf16 v[12:15], v[144:147], v[156:159], v[12:15]
	v_sub_f32_e32 v236, v236, v89
	v_sub_f32_e32 v237, v237, v89
	v_sub_f32_e32 v238, v238, v89
	v_sub_f32_e32 v239, v239, v89
	v_mfma_f32_16x16x32_bf16 v[16:19], v[148:151], v[156:159], v[16:19]
	v_exp_f32_e32 v232, v232
	v_exp_f32_e32 v233, v233
	v_exp_f32_e32 v234, v234
	v_exp_f32_e32 v235, v235
	v_mfma_f32_16x16x32_bf16 v[20:23], v[152:155], v[156:159], v[20:23]
	v_exp_f32_e32 v236, v236
	v_exp_f32_e32 v237, v237
	v_exp_f32_e32 v238, v238
	v_exp_f32_e32 v239, v239
	v_mfma_f32_16x16x32_bf16 v[72:75], v[176:179], v[156:159], v[72:75]
	s_nop 0
	v_cvt_pk_bf16_f32 v232, v232, v233
	v_cvt_pk_bf16_f32 v233, v234, v235
	v_cvt_pk_bf16_f32 v234, v236, v237
	v_cvt_pk_bf16_f32 v235, v238, v239
	s_waitcnt lgkmcnt(0)
	v_mfma_f32_16x16x32_bf16 v[198:201], v[168:171], v[116:119], v[198:201]
	v_add_f32_e32 v1, 0x41000000, v90
	v_max3_f32 v3, v180, v181, v182
	v_mfma_f32_16x16x32_bf16 v[202:205], v[226:229], v[116:119], v[202:205]
	v_max3_f32 v4, v183, v184, v185
	v_max3_f32 v3, v3, v186, v187
	v_mfma_f32_16x16x32_bf16 v[198:201], v[172:175], v[120:123], v[198:201]
	v_max_f32_e32 v3, v3, v4
	v_cmp_gt_f32_e32 vcc, v3, v1
	v_mfma_f32_16x16x32_bf16 v[202:205], v[244:247], v[120:123], v[202:205]
	s_cbranch_vccz .La0_nr_b15_2
	ds_bpermute_b32 v4, v194, v3
	s_waitcnt lgkmcnt(0)
	v_max_f32_e32 v3, v3, v4
	ds_bpermute_b32 v4, v195, v3
	s_waitcnt lgkmcnt(0)
	v_max3_f32 v3, v3, v4, v90
	v_sub_f32_e32 v4, v90, v3
	v_exp_f32_e32 v4, v4
	v_mov_b32_e32 v90, v3
	s_nop 0
	v_mul_f32_e32 v80, v80, v4
	v_mul_f32_e32 v81, v81, v4
	v_mul_f32_e32 v82, v82, v4
	v_mul_f32_e32 v83, v83, v4
	v_mul_f32_e32 v40, v40, v4
	v_mul_f32_e32 v41, v41, v4
	v_mul_f32_e32 v42, v42, v4
	v_mul_f32_e32 v43, v43, v4
	v_mul_f32_e32 v44, v44, v4
	v_mul_f32_e32 v45, v45, v4
	v_mul_f32_e32 v46, v46, v4
	v_mul_f32_e32 v47, v47, v4
	v_mul_f32_e32 v48, v48, v4
	v_mul_f32_e32 v49, v49, v4
	v_mul_f32_e32 v50, v50, v4
	v_mul_f32_e32 v51, v51, v4
	v_mul_f32_e32 v52, v52, v4
	v_mul_f32_e32 v53, v53, v4
	v_mul_f32_e32 v54, v54, v4
	v_mul_f32_e32 v55, v55, v4

.La0_pb_7:
	ds_read_b128 v[156:159], v167 offset:12288
	ds_read_b128 v[160:163], v167 offset:13312
	ds_read_b128 v[232:235], v167 offset:8192
	ds_read_b128 v[236:239], v167 offset:9216
	ds_read_b128 v[180:183], v167 offset:4096
	ds_read_b128 v[184:187], v167 offset:5120
	s_waitcnt lgkmcnt(4)
	v_mfma_f32_16x16x32_bf16 v[156:159], v[168:171], v[92:95], v[156:159]
	v_mfma_f32_16x16x32_bf16 v[160:163], v[226:229], v[92:95], v[160:163]
	v_mfma_f32_16x16x32_bf16 v[156:159], v[172:175], v[96:99], v[156:159]
	v_mfma_f32_16x16x32_bf16 v[160:163], v[244:247], v[96:99], v[160:163]
	s_waitcnt lgkmcnt(2)
	v_mfma_f32_16x16x32_bf16 v[232:235], v[168:171], v[100:103], v[232:235]
	v_mfma_f32_16x16x32_bf16 v[236:239], v[226:229], v[100:103], v[236:239]
	v_mfma_f32_16x16x32_bf16 v[232:235], v[172:175], v[104:107], v[232:235]
	v_mfma_f32_16x16x32_bf16 v[236:239], v[244:247], v[104:107], v[236:239]
	v_add_f32_e32 v164, 0x41000000, v88
	s_nop 3
	v_max3_f32 v165, v156, v157, v158
	v_max3_f32 v166, v159, v160, v161
	v_max3_f32 v165, v165, v162, v163
	v_max_f32_e32 v165, v165, v166
	v_cmp_gt_f32_e32 vcc, v165, v164
	s_cbranch_vccz .La0_nr_b7_0
	ds_bpermute_b32 v166, v194, v165
	s_waitcnt lgkmcnt(0)
	v_max_f32_e32 v165, v165, v166
	ds_bpermute_b32 v166, v195, v165
	s_waitcnt lgkmcnt(0)
	v_max3_f32 v165, v165, v166, v88
	v_sub_f32_e32 v166, v88, v165
	v_exp_f32_e32 v166, v166
	v_mov_b32_e32 v88, v165
	s_nop 0
	v_mul_f32_e32 v72, v72, v166
	v_mul_f32_e32 v73, v73, v166
	v_mul_f32_e32 v74, v74, v166
	v_mul_f32_e32 v75, v75, v166
	v_mul_f32_e32 v8, v8, v166
	v_mul_f32_e32 v9, v9, v166
	v_mul_f32_e32 v10, v10, v166
	v_mul_f32_e32 v11, v11, v166
	v_mul_f32_e32 v12, v12, v166
	v_mul_f32_e32 v13, v13, v166
	v_mul_f32_e32 v14, v14, v166
	v_mul_f32_e32 v15, v15, v166
	v_mul_f32_e32 v16, v16, v166
	v_mul_f32_e32 v17, v17, v166
	v_mul_f32_e32 v18, v18, v166
	v_mul_f32_e32 v19, v19, v166
	v_mul_f32_e32 v20, v20, v166
	v_mul_f32_e32 v21, v21, v166
	v_mul_f32_e32 v22, v22, v166
	v_mul_f32_e32 v23, v23, v166
.La0_nr_b7_0:
	v_sub_f32_e32 v156, v156, v88
	v_sub_f32_e32 v157, v157, v88
	v_sub_f32_e32 v158, v158, v88
	v_sub_f32_e32 v159, v159, v88
	v_sub_f32_e32 v160, v160, v88
	v_sub_f32_e32 v161, v161, v88
	v_sub_f32_e32 v162, v162, v88
	v_sub_f32_e32 v163, v163, v88
	v_exp_f32_e32 v156, v156
	v_exp_f32_e32 v157, v157
	v_exp_f32_e32 v158, v158
	v_exp_f32_e32 v159, v159
	v_exp_f32_e32 v160, v160
	v_exp_f32_e32 v161, v161
	v_exp_f32_e32 v162, v162
	v_exp_f32_e32 v163, v163
	s_nop 0
	v_cvt_pk_bf16_f32 v156, v156, v157
	v_cvt_pk_bf16_f32 v157, v158, v159
	v_cvt_pk_bf16_f32 v158, v160, v161
	v_cvt_pk_bf16_f32 v159, v162, v163
	s_waitcnt lgkmcnt(0)
	v_mfma_f32_16x16x32_bf16 v[180:183], v[168:171], v[108:111], v[180:183]
	v_add_f32_e32 v240, 0x41000000, v89
	v_max3_f32 v241, v232, v233, v234
	v_mfma_f32_16x16x32_bf16 v[184:187], v[226:229], v[108:111], v[184:187]
	v_max3_f32 v242, v235, v236, v237
	v_max3_f32 v241, v241, v238, v239
	v_mfma_f32_16x16x32_bf16 v[180:183], v[172:175], v[112:115], v[180:183]
	v_max_f32_e32 v241, v241, v242
	v_cmp_gt_f32_e32 vcc, v241, v240
	v_mfma_f32_16x16x32_bf16 v[184:187], v[244:247], v[112:115], v[184:187]
	s_cbranch_vccz .La0_nr_b7_1
	ds_bpermute_b32 v242, v194, v241
	s_waitcnt lgkmcnt(0)
	v_max_f32_e32 v241, v241, v242
	ds_bpermute_b32 v242, v195, v241
	s_waitcnt lgkmcnt(0)
	v_max3_f32 v241, v241, v242, v89
	v_sub_f32_e32 v242, v89, v241
	v_exp_f32_e32 v242, v242
	v_mov_b32_e32 v89, v241
	s_nop 0
	v_mul_f32_e32 v76, v76, v242
	v_mul_f32_e32 v77, v77, v242
	v_mul_f32_e32 v78, v78, v242
	v_mul_f32_e32 v79, v79, v242
	v_mul_f32_e32 v24, v24, v242
	v_mul_f32_e32 v25, v25, v242
	v_mul_f32_e32 v26, v26, v242
	v_mul_f32_e32 v27, v27, v242
	v_mul_f32_e32 v28, v28, v242
	v_mul_f32_e32 v29, v29, v242
	v_mul_f32_e32 v30, v30, v242
	v_mul_f32_e32 v31, v31, v242
	v_mul_f32_e32 v32, v32, v242
	v_mul_f32_e32 v33, v33, v242
	v_mul_f32_e32 v34, v34, v242
	v_mul_f32_e32 v35, v35, v242
	v_mul_f32_e32 v36, v36, v242
	v_mul_f32_e32 v37, v37, v242
	v_mul_f32_e32 v38, v38, v242
	v_mul_f32_e32 v39, v39, v242

.La0_pb_14:
	ds_read_b128 v[232:235], v167 offset:8192
	ds_read_b128 v[236:239], v167 offset:9216
	ds_read_b128 v[180:183], v167 offset:4096
	ds_read_b128 v[184:187], v167 offset:5120
	ds_read_b128 v[198:201], v167 offset:0
	ds_read_b128 v[202:205], v167 offset:1024
	s_waitcnt lgkmcnt(4)
	v_mfma_f32_16x16x32_bf16 v[232:235], v[168:171], v[100:103], v[232:235]
	v_mfma_f32_16x16x32_bf16 v[236:239], v[226:229], v[100:103], v[236:239]
	v_mfma_f32_16x16x32_bf16 v[232:235], v[172:175], v[104:107], v[232:235]
	v_mfma_f32_16x16x32_bf16 v[236:239], v[244:247], v[104:107], v[236:239]
	s_waitcnt lgkmcnt(2)
	v_mfma_f32_16x16x32_bf16 v[180:183], v[168:171], v[108:111], v[180:183]
	v_mfma_f32_16x16x32_bf16 v[184:187], v[226:229], v[108:111], v[184:187]
	v_mfma_f32_16x16x32_bf16 v[180:183], v[172:175], v[112:115], v[180:183]
	v_mfma_f32_16x16x32_bf16 v[184:187], v[244:247], v[112:115], v[184:187]
	v_add_f32_e32 v240, 0x41000000, v89
	s_nop 3
	v_max3_f32 v241, v232, v233, v234
	v_max3_f32 v242, v235, v236, v237
	v_max3_f32 v241, v241, v238, v239
	v_max_f32_e32 v241, v241, v242
	v_cmp_gt_f32_e32 vcc, v241, v240
	s_cbranch_vccz .La0_nr_b14_1
	ds_bpermute_b32 v242, v194, v241
	s_waitcnt lgkmcnt(0)
	v_max_f32_e32 v241, v241, v242
	ds_bpermute_b32 v242, v195, v241
	s_waitcnt lgkmcnt(0)
	v_max3_f32 v241, v241, v242, v89
	v_sub_f32_e32 v242, v89, v241
	v_exp_f32_e32 v242, v242
	v_mov_b32_e32 v89, v241
	s_nop 0
	v_mul_f32_e32 v76, v76, v242
	v_mul_f32_e32 v77, v77, v242
	v_mul_f32_e32 v78, v78, v242
	v_mul_f32_e32 v79, v79, v242
	v_mul_f32_e32 v24, v24, v242
	v_mul_f32_e32 v25, v25, v242
	v_mul_f32_e32 v26, v26, v242
	v_mul_f32_e32 v27, v27, v242
	v_mul_f32_e32 v28, v28, v242
	v_mul_f32_e32 v29, v29, v242
	v_mul_f32_e32 v30, v30, v242
	v_mul_f32_e32 v31, v31, v242
	v_mul_f32_e32 v32, v32, v242
	v_mul_f32_e32 v33, v33, v242
	v_mul_f32_e32 v34, v34, v242
	v_mul_f32_e32 v35, v35, v242
	v_mul_f32_e32 v36, v36, v242
	v_mul_f32_e32 v37, v37, v242
	v_mul_f32_e32 v38, v38, v242
	v_mul_f32_e32 v39, v39, v242
.La0_nr_b14_1:
	v_sub_f32_e32 v232, v232, v89
	v_sub_f32_e32 v233, v233, v89
	v_sub_f32_e32 v234, v234, v89
	v_sub_f32_e32 v235, v235, v89
	v_sub_f32_e32 v236, v236, v89
	v_sub_f32_e32 v237, v237, v89
	v_sub_f32_e32 v238, v238, v89
	v_sub_f32_e32 v239, v239, v89
	v_exp_f32_e32 v232, v232
	v_exp_f32_e32 v233, v233
	v_exp_f32_e32 v234, v234
	v_exp_f32_e32 v235, v235
	v_exp_f32_e32 v236, v236
	v_exp_f32_e32 v237, v237
	v_exp_f32_e32 v238, v238
	v_exp_f32_e32 v239, v239
	s_nop 0
	v_cvt_pk_bf16_f32 v232, v232, v233
	v_cvt_pk_bf16_f32 v233, v234, v235
	v_cvt_pk_bf16_f32 v234, v236, v237
	v_cvt_pk_bf16_f32 v235, v238, v239
	s_waitcnt lgkmcnt(0)
	v_mfma_f32_16x16x32_bf16 v[198:201], v[168:171], v[116:119], v[198:201]
	v_add_f32_e32 v1, 0x41000000, v90
	v_max3_f32 v3, v180, v181, v182
	v_mfma_f32_16x16x32_bf16 v[202:205], v[226:229], v[116:119], v[202:205]
	v_max3_f32 v4, v183, v184, v185
	v_max3_f32 v3, v3, v186, v187
	v_mfma_f32_16x16x32_bf16 v[198:201], v[172:175], v[120:123], v[198:201]
	v_max_f32_e32 v3, v3, v4
	v_cmp_gt_f32_e32 vcc, v3, v1
	v_mfma_f32_16x16x32_bf16 v[202:205], v[244:247], v[120:123], v[202:205]
	s_cbranch_vccz .La0_nr_b14_2
	ds_bpermute_b32 v4, v194, v3
	s_waitcnt lgkmcnt(0)
	v_max_f32_e32 v3, v3, v4
	ds_bpermute_b32 v4, v195, v3
	s_waitcnt lgkmcnt(0)
	v_max3_f32 v3, v3, v4, v90
	v_sub_f32_e32 v4, v90, v3
	v_exp_f32_e32 v4, v4
	v_mov_b32_e32 v90, v3
	s_nop 0
	v_mul_f32_e32 v80, v80, v4
	v_mul_f32_e32 v81, v81, v4
	v_mul_f32_e32 v82, v82, v4
	v_mul_f32_e32 v83, v83, v4
	v_mul_f32_e32 v40, v40, v4
	v_mul_f32_e32 v41, v41, v4
	v_mul_f32_e32 v42, v42, v4
	v_mul_f32_e32 v43, v43, v4
	v_mul_f32_e32 v44, v44, v4
	v_mul_f32_e32 v45, v45, v4
	v_mul_f32_e32 v46, v46, v4
	v_mul_f32_e32 v47, v47, v4
	v_mul_f32_e32 v48, v48, v4
	v_mul_f32_e32 v49, v49, v4
	v_mul_f32_e32 v50, v50, v4
	v_mul_f32_e32 v51, v51, v4
	v_mul_f32_e32 v52, v52, v4
	v_mul_f32_e32 v53, v53, v4
	v_mul_f32_e32 v54, v54, v4
	v_mul_f32_e32 v55, v55, v4

.La0_pb_3:
	ds_read_b128 v[156:159], v167 offset:12288
	ds_read_b128 v[160:163], v167 offset:13312
	ds_read_b128 v[232:235], v167 offset:8192
	ds_read_b128 v[236:239], v167 offset:9216
	s_waitcnt lgkmcnt(2)
	v_mfma_f32_16x16x32_bf16 v[156:159], v[168:171], v[92:95], v[156:159]
	v_mfma_f32_16x16x32_bf16 v[160:163], v[226:229], v[92:95], v[160:163]
	v_mfma_f32_16x16x32_bf16 v[156:159], v[172:175], v[96:99], v[156:159]
	v_mfma_f32_16x16x32_bf16 v[160:163], v[244:247], v[96:99], v[160:163]
	s_waitcnt lgkmcnt(0)
	v_mfma_f32_16x16x32_bf16 v[232:235], v[168:171], v[100:103], v[232:235]
	v_mfma_f32_16x16x32_bf16 v[236:239], v[226:229], v[100:103], v[236:239]
	v_mfma_f32_16x16x32_bf16 v[232:235], v[172:175], v[104:107], v[232:235]
	v_mfma_f32_16x16x32_bf16 v[236:239], v[244:247], v[104:107], v[236:239]
	v_add_f32_e32 v164, 0x41000000, v88
	s_nop 3
	v_max3_f32 v165, v156, v157, v158
	v_max3_f32 v166, v159, v160, v161
	v_max3_f32 v165, v165, v162, v163
	v_max_f32_e32 v165, v165, v166
	v_cmp_gt_f32_e32 vcc, v165, v164
	s_cbranch_vccz .La0_nr_b3_0
	ds_bpermute_b32 v166, v194, v165
	s_waitcnt lgkmcnt(0)
	v_max_f32_e32 v165, v165, v166
	ds_bpermute_b32 v166, v195, v165
	s_waitcnt lgkmcnt(0)
	v_max3_f32 v165, v165, v166, v88
	v_sub_f32_e32 v166, v88, v165
	v_exp_f32_e32 v166, v166
	v_mov_b32_e32 v88, v165
	s_nop 0
	v_mul_f32_e32 v72, v72, v166
	v_mul_f32_e32 v73, v73, v166
	v_mul_f32_e32 v74, v74, v166
	v_mul_f32_e32 v75, v75, v166
	v_mul_f32_e32 v8, v8, v166
	v_mul_f32_e32 v9, v9, v166
	v_mul_f32_e32 v10, v10, v166
	v_mul_f32_e32 v11, v11, v166
	v_mul_f32_e32 v12, v12, v166
	v_mul_f32_e32 v13, v13, v166
	v_mul_f32_e32 v14, v14, v166
	v_mul_f32_e32 v15, v15, v166
	v_mul_f32_e32 v16, v16, v166
	v_mul_f32_e32 v17, v17, v166
	v_mul_f32_e32 v18, v18, v166
	v_mul_f32_e32 v19, v19, v166
	v_mul_f32_e32 v20, v20, v166
	v_mul_f32_e32 v21, v21, v166
	v_mul_f32_e32 v22, v22, v166
	v_mul_f32_e32 v23, v23, v166

.La0_pb_12:
	ds_read_b128 v[180:183], v167 offset:4096
	ds_read_b128 v[184:187], v167 offset:5120
	ds_read_b128 v[198:201], v167 offset:0
	ds_read_b128 v[202:205], v167 offset:1024
	s_waitcnt lgkmcnt(2)
	v_mfma_f32_16x16x32_bf16 v[180:183], v[168:171], v[108:111], v[180:183]
	v_mfma_f32_16x16x32_bf16 v[184:187], v[226:229], v[108:111], v[184:187]
	v_mfma_f32_16x16x32_bf16 v[180:183], v[172:175], v[112:115], v[180:183]
	v_mfma_f32_16x16x32_bf16 v[184:187], v[244:247], v[112:115], v[184:187]
	s_waitcnt lgkmcnt(0)
	v_mfma_f32_16x16x32_bf16 v[198:201], v[168:171], v[116:119], v[198:201]
	v_mfma_f32_16x16x32_bf16 v[202:205], v[226:229], v[116:119], v[202:205]
	v_mfma_f32_16x16x32_bf16 v[198:201], v[172:175], v[120:123], v[198:201]
	v_mfma_f32_16x16x32_bf16 v[202:205], v[244:247], v[120:123], v[202:205]
	v_add_f32_e32 v1, 0x41000000, v90
	s_nop 3
	v_max3_f32 v3, v180, v181, v182
	v_max3_f32 v4, v183, v184, v185
	v_max3_f32 v3, v3, v186, v187
	v_max_f32_e32 v3, v3, v4
	v_cmp_gt_f32_e32 vcc, v3, v1
	s_cbranch_vccz .La0_nr_b12_2
	ds_bpermute_b32 v4, v194, v3
	s_waitcnt lgkmcnt(0)
	v_max_f32_e32 v3, v3, v4
	ds_bpermute_b32 v4, v195, v3
	s_waitcnt lgkmcnt(0)
	v_max3_f32 v3, v3, v4, v90
	v_sub_f32_e32 v4, v90, v3
	v_exp_f32_e32 v4, v4
	v_mov_b32_e32 v90, v3
	s_nop 0
	v_mul_f32_e32 v80, v80, v4
	v_mul_f32_e32 v81, v81, v4
	v_mul_f32_e32 v82, v82, v4
	v_mul_f32_e32 v83, v83, v4
	v_mul_f32_e32 v40, v40, v4
	v_mul_f32_e32 v41, v41, v4
	v_mul_f32_e32 v42, v42, v4
	v_mul_f32_e32 v43, v43, v4
	v_mul_f32_e32 v44, v44, v4
	v_mul_f32_e32 v45, v45, v4
	v_mul_f32_e32 v46, v46, v4
	v_mul_f32_e32 v47, v47, v4
	v_mul_f32_e32 v48, v48, v4
	v_mul_f32_e32 v49, v49, v4
	v_mul_f32_e32 v50, v50, v4
	v_mul_f32_e32 v51, v51, v4
	v_mul_f32_e32 v52, v52, v4
	v_mul_f32_e32 v53, v53, v4
	v_mul_f32_e32 v54, v54, v4
	v_mul_f32_e32 v55, v55, v4

.La0_pb_1:
	ds_read_b128 v[156:159], v167 offset:12288
	ds_read_b128 v[160:163], v167 offset:13312
	s_waitcnt lgkmcnt(0)
	v_mfma_f32_16x16x32_bf16 v[156:159], v[168:171], v[92:95], v[156:159]
	v_mfma_f32_16x16x32_bf16 v[160:163], v[226:229], v[92:95], v[160:163]
	v_mfma_f32_16x16x32_bf16 v[156:159], v[172:175], v[96:99], v[156:159]
	v_mfma_f32_16x16x32_bf16 v[160:163], v[244:247], v[96:99], v[160:163]
	v_add_f32_e32 v164, 0x41000000, v88
	s_nop 7
	v_max3_f32 v165, v156, v157, v158
	v_max3_f32 v166, v159, v160, v161
	v_max3_f32 v165, v165, v162, v163
	v_max_f32_e32 v165, v165, v166
	v_cmp_gt_f32_e32 vcc, v165, v164
	s_cbranch_vccz .La0_nr_b1_0
	ds_bpermute_b32 v166, v194, v165
	s_waitcnt lgkmcnt(0)
	v_max_f32_e32 v165, v165, v166
	ds_bpermute_b32 v166, v195, v165
	s_waitcnt lgkmcnt(0)
	v_max3_f32 v165, v165, v166, v88
	v_sub_f32_e32 v166, v88, v165
	v_exp_f32_e32 v166, v166
	v_mov_b32_e32 v88, v165
	s_nop 0
	v_mul_f32_e32 v72, v72, v166
	v_mul_f32_e32 v73, v73, v166
	v_mul_f32_e32 v74, v74, v166
	v_mul_f32_e32 v75, v75, v166
	v_mul_f32_e32 v8, v8, v166
	v_mul_f32_e32 v9, v9, v166
	v_mul_f32_e32 v10, v10, v166
	v_mul_f32_e32 v11, v11, v166
	v_mul_f32_e32 v12, v12, v166
	v_mul_f32_e32 v13, v13, v166
	v_mul_f32_e32 v14, v14, v166
	v_mul_f32_e32 v15, v15, v166
	v_mul_f32_e32 v16, v16, v166
	v_mul_f32_e32 v17, v17, v166
	v_mul_f32_e32 v18, v18, v166
	v_mul_f32_e32 v19, v19, v166
	v_mul_f32_e32 v20, v20, v166
	v_mul_f32_e32 v21, v21, v166
	v_mul_f32_e32 v22, v22, v166
	v_mul_f32_e32 v23, v23, v166

.La0_pb_8:
	ds_read_b128 v[198:201], v167 offset:0
	ds_read_b128 v[202:205], v167 offset:1024
	s_waitcnt lgkmcnt(0)
	v_mfma_f32_16x16x32_bf16 v[198:201], v[168:171], v[116:119], v[198:201]
	v_mfma_f32_16x16x32_bf16 v[202:205], v[226:229], v[116:119], v[202:205]
	v_mfma_f32_16x16x32_bf16 v[198:201], v[172:175], v[120:123], v[198:201]
	v_mfma_f32_16x16x32_bf16 v[202:205], v[244:247], v[120:123], v[202:205]
	v_add_f32_e32 v5, 0x41000000, v91
	s_nop 7
	v_max3_f32 v7, v198, v199, v200
	v_max3_f32 v206, v201, v202, v203
	v_max3_f32 v7, v7, v204, v205
	v_max_f32_e32 v7, v7, v206
	v_cmp_gt_f32_e32 vcc, v7, v5
	s_cbranch_vccz .La0_nr_b8_3
	ds_bpermute_b32 v206, v194, v7
	s_waitcnt lgkmcnt(0)
	v_max_f32_e32 v7, v7, v206
	ds_bpermute_b32 v206, v195, v7
	s_waitcnt lgkmcnt(0)
	v_max3_f32 v7, v7, v206, v91
	v_sub_f32_e32 v206, v91, v7
	v_exp_f32_e32 v206, v206
	v_mov_b32_e32 v91, v7
	s_nop 0
	v_mul_f32_e32 v84, v84, v206
	v_mul_f32_e32 v85, v85, v206
	v_mul_f32_e32 v86, v86, v206
	v_mul_f32_e32 v87, v87, v206
	v_mul_f32_e32 v56, v56, v206
	v_mul_f32_e32 v57, v57, v206
	v_mul_f32_e32 v58, v58, v206
	v_mul_f32_e32 v59, v59, v206
	v_mul_f32_e32 v60, v60, v206
	v_mul_f32_e32 v61, v61, v206
	v_mul_f32_e32 v62, v62, v206
	v_mul_f32_e32 v63, v63, v206
	v_mul_f32_e32 v64, v64, v206
	v_mul_f32_e32 v65, v65, v206
	v_mul_f32_e32 v66, v66, v206
	v_mul_f32_e32 v67, v67, v206
	v_mul_f32_e32 v68, v68, v206
	v_mul_f32_e32 v69, v69, v206
	v_mul_f32_e32 v70, v70, v206
	v_mul_f32_e32 v71, v71, v206

.La0_rowdone_b:
.La0_ss_done:
	s_add_i32 s62, s62, 1
	s_add_i32 s44, s44, 1
	s_cmp_lt_u32 s44, s45
	s_cbranch_scc1 .La0_ss
	s_cmp_lt_u32 s63, 1
	s_cbranch_scc0 .La0_last_round
	s_add_i32 s98, s41, 8
	s_add_i32 s5, s98, s54
	s_add_i32 s5, s5, 0
	s_lshl_b32 s5, s5, 6
	s_lshl_b32 s6, s53, 4
	s_add_i32 s5, s5, s6
	s_lshl_b32 s5, s5, 7
	s_add_u32 s0, s30, s5
	s_addc_u32 s1, s31, 0
	global_load_dwordx4 v[92:95], v193, s[0:1]
	global_load_dwordx4 v[96:99], v193, s[0:1] offset:16
	s_add_i32 s5, s98, s54
	s_add_i32 s5, s5, 2
	s_lshl_b32 s5, s5, 6
	s_lshl_b32 s6, s53, 4
	s_add_i32 s5, s5, s6
	s_lshl_b32 s5, s5, 7
	s_add_u32 s0, s30, s5
	s_addc_u32 s1, s31, 0
	global_load_dwordx4 v[100:103], v193, s[0:1]
	global_load_dwordx4 v[104:107], v193, s[0:1] offset:16
	s_add_i32 s5, s98, s54
	s_add_i32 s5, s5, 4
	s_lshl_b32 s5, s5, 6
	s_lshl_b32 s6, s53, 4
	s_add_i32 s5, s5, s6
	s_lshl_b32 s5, s5, 7
	s_add_u32 s0, s30, s5
	s_addc_u32 s1, s31, 0
	global_load_dwordx4 v[108:111], v193, s[0:1]
	global_load_dwordx4 v[112:115], v193, s[0:1] offset:16
	s_add_i32 s5, s98, s54
	s_add_i32 s5, s5, 6
	s_lshl_b32 s5, s5, 6
	s_lshl_b32 s6, s53, 4
	s_add_i32 s5, s5, s6
	s_lshl_b32 s5, s5, 7
	s_add_u32 s0, s30, s5
	s_addc_u32 s1, s31, 0
	global_load_dwordx4 v[116:119], v193, s[0:1]
	global_load_dwordx4 v[120:123], v193, s[0:1] offset:16
	s_waitcnt vmcnt(12)
.La0_dummy0:
	v_rcp_f32_e32 v172, v72
	v_lshlrev_b32_e32 v140, 16, v210
	v_and_b32_e32 v141, 0xffff0000, v210
	v_lshlrev_b32_e32 v142, 16, v211
	v_and_b32_e32 v143, 0xffff0000, v211
	v_lshlrev_b32_e32 v144, 16, v212
	v_and_b32_e32 v145, 0xffff0000, v212
	v_lshlrev_b32_e32 v146, 16, v213
	v_and_b32_e32 v147, 0xffff0000, v213
	v_lshlrev_b32_e32 v148, 16, v214
	v_and_b32_e32 v149, 0xffff0000, v214
	v_lshlrev_b32_e32 v150, 16, v215
	v_and_b32_e32 v151, 0xffff0000, v215
	v_lshlrev_b32_e32 v152, 16, v216
	v_and_b32_e32 v153, 0xffff0000, v216
	v_lshlrev_b32_e32 v154, 16, v217
	v_and_b32_e32 v155, 0xffff0000, v217
	v_mul_f32_e32 v180, 0xbfb8aa3b, v140
	v_mul_f32_e32 v181, 0xbfb8aa3b, v141
	v_mul_f32_e32 v182, 0xbfb8aa3b, v142
	v_mul_f32_e32 v183, 0xbfb8aa3b, v143
	v_mul_f32_e32 v184, 0xbfb8aa3b, v144
	v_mul_f32_e32 v185, 0xbfb8aa3b, v145
	v_mul_f32_e32 v186, 0xbfb8aa3b, v146
	v_mul_f32_e32 v187, 0xbfb8aa3b, v147
	v_mul_f32_e32 v198, 0xbfb8aa3b, v148
	v_mul_f32_e32 v199, 0xbfb8aa3b, v149
	v_mul_f32_e32 v200, 0xbfb8aa3b, v150
	v_mul_f32_e32 v201, 0xbfb8aa3b, v151
	v_mul_f32_e32 v202, 0xbfb8aa3b, v152
	v_mul_f32_e32 v203, 0xbfb8aa3b, v153
	v_mul_f32_e32 v204, 0xbfb8aa3b, v154
	v_mul_f32_e32 v205, 0xbfb8aa3b, v155
	v_exp_f32_e32 v180, v180
	v_exp_f32_e32 v181, v181
	v_exp_f32_e32 v182, v182
	v_exp_f32_e32 v183, v183
	v_exp_f32_e32 v184, v184
	v_exp_f32_e32 v185, v185
	v_exp_f32_e32 v186, v186
	v_exp_f32_e32 v187, v187
	v_exp_f32_e32 v198, v198
	v_exp_f32_e32 v199, v199
	v_exp_f32_e32 v200, v200
	v_exp_f32_e32 v201, v201
	v_exp_f32_e32 v202, v202
	v_exp_f32_e32 v203, v203
	v_exp_f32_e32 v204, v204
	v_exp_f32_e32 v205, v205
	v_mul_f32_e32 v8, v8, v172
	v_mul_f32_e32 v9, v9, v172
	v_mul_f32_e32 v10, v10, v172
	v_mul_f32_e32 v11, v11, v172
	v_mul_f32_e32 v12, v12, v172
	v_mul_f32_e32 v13, v13, v172
	v_mul_f32_e32 v14, v14, v172
	v_mul_f32_e32 v15, v15, v172
	v_mul_f32_e32 v16, v16, v172
	v_mul_f32_e32 v17, v17, v172
	v_mul_f32_e32 v18, v18, v172
	v_mul_f32_e32 v19, v19, v172
	v_mul_f32_e32 v20, v20, v172
	v_mul_f32_e32 v21, v21, v172
	v_mul_f32_e32 v22, v22, v172
	v_mul_f32_e32 v23, v23, v172
	v_add_f32_e32 v180, 1.0, v180
	v_add_f32_e32 v181, 1.0, v181
	v_add_f32_e32 v182, 1.0, v182
	v_add_f32_e32 v183, 1.0, v183
	v_add_f32_e32 v184, 1.0, v184
	v_add_f32_e32 v185, 1.0, v185
	v_add_f32_e32 v186, 1.0, v186
	v_add_f32_e32 v187, 1.0, v187
	v_add_f32_e32 v198, 1.0, v198
	v_add_f32_e32 v199, 1.0, v199
	v_add_f32_e32 v200, 1.0, v200
	v_add_f32_e32 v201, 1.0, v201
	v_add_f32_e32 v202, 1.0, v202
	v_add_f32_e32 v203, 1.0, v203
	v_add_f32_e32 v204, 1.0, v204
	v_add_f32_e32 v205, 1.0, v205
	v_rcp_f32_e32 v180, v180
	v_rcp_f32_e32 v181, v181
	v_rcp_f32_e32 v182, v182
	v_rcp_f32_e32 v183, v183
	v_rcp_f32_e32 v184, v184
	v_rcp_f32_e32 v185, v185
	v_rcp_f32_e32 v186, v186
	v_rcp_f32_e32 v187, v187
	v_rcp_f32_e32 v198, v198
	v_rcp_f32_e32 v199, v199
	v_rcp_f32_e32 v200, v200
	v_rcp_f32_e32 v201, v201
	v_rcp_f32_e32 v202, v202
	v_rcp_f32_e32 v203, v203
	v_rcp_f32_e32 v204, v204
	v_rcp_f32_e32 v205, v205
	v_mul_f32_e32 v8, v8, v140
	v_mul_f32_e32 v9, v9, v141
	v_mul_f32_e32 v10, v10, v142
	v_mul_f32_e32 v11, v11, v143
	v_mul_f32_e32 v12, v12, v144
	v_mul_f32_e32 v13, v13, v145
	v_mul_f32_e32 v14, v14, v146
	v_mul_f32_e32 v15, v15, v147
	v_mul_f32_e32 v16, v16, v148
	v_mul_f32_e32 v17, v17, v149
	v_mul_f32_e32 v18, v18, v150
	v_mul_f32_e32 v19, v19, v151
	v_mul_f32_e32 v20, v20, v152
	v_mul_f32_e32 v21, v21, v153
	v_mul_f32_e32 v22, v22, v154
	v_mul_f32_e32 v23, v23, v155
	v_mul_f32_e32 v8, v8, v180
	v_mul_f32_e32 v9, v9, v181
	v_mul_f32_e32 v10, v10, v182
	v_mul_f32_e32 v11, v11, v183
	v_mul_f32_e32 v12, v12, v184
	v_mul_f32_e32 v13, v13, v185
	v_mul_f32_e32 v14, v14, v186
	v_mul_f32_e32 v15, v15, v187
	v_mul_f32_e32 v16, v16, v198
	v_mul_f32_e32 v17, v17, v199
	v_mul_f32_e32 v18, v18, v200
	v_mul_f32_e32 v19, v19, v201
	v_mul_f32_e32 v20, v20, v202
	v_mul_f32_e32 v21, v21, v203
	v_mul_f32_e32 v22, v22, v204
	v_mul_f32_e32 v23, v23, v205
	v_cvt_pk_bf16_f32 v164, v8, v9
	v_cvt_pk_bf16_f32 v165, v10, v11
	v_cvt_pk_bf16_f32 v166, v12, v13
	v_cvt_pk_bf16_f32 v167, v14, v15
	v_cvt_pk_bf16_f32 v168, v16, v17
	v_cvt_pk_bf16_f32 v169, v18, v19
	v_cvt_pk_bf16_f32 v170, v20, v21
	v_cvt_pk_bf16_f32 v171, v22, v23
	s_add_i32 s5, s41, s54
	s_add_i32 s5, s5, 0
	s_lshl_b32 s5, s5, 17
	s_add_u32 s0, s58, s5
	s_addc_u32 s1, s59, 0
	global_store_dwordx4 v196, v[164:167], s[0:1]
	global_store_dwordx4 v196, v[168:171], s[0:1] offset:16
	s_nop 1
	v_rcp_f32_e32 v172, v76
	v_lshlrev_b32_e32 v140, 16, v218
	v_and_b32_e32 v141, 0xffff0000, v218
	v_lshlrev_b32_e32 v142, 16, v219
	v_and_b32_e32 v143, 0xffff0000, v219
	v_lshlrev_b32_e32 v144, 16, v220
	v_and_b32_e32 v145, 0xffff0000, v220
	v_lshlrev_b32_e32 v146, 16, v221
	v_and_b32_e32 v147, 0xffff0000, v221
	v_lshlrev_b32_e32 v148, 16, v222
	v_and_b32_e32 v149, 0xffff0000, v222
	v_lshlrev_b32_e32 v150, 16, v223
	v_and_b32_e32 v151, 0xffff0000, v223
	v_lshlrev_b32_e32 v152, 16, v224
	v_and_b32_e32 v153, 0xffff0000, v224
	v_lshlrev_b32_e32 v154, 16, v225
	v_and_b32_e32 v155, 0xffff0000, v225
	v_mul_f32_e32 v180, 0xbfb8aa3b, v140
	v_mul_f32_e32 v181, 0xbfb8aa3b, v141
	v_mul_f32_e32 v182, 0xbfb8aa3b, v142
	v_mul_f32_e32 v183, 0xbfb8aa3b, v143
	v_mul_f32_e32 v184, 0xbfb8aa3b, v144
	v_mul_f32_e32 v185, 0xbfb8aa3b, v145
	v_mul_f32_e32 v186, 0xbfb8aa3b, v146
	v_mul_f32_e32 v187, 0xbfb8aa3b, v147
	v_mul_f32_e32 v198, 0xbfb8aa3b, v148
	v_mul_f32_e32 v199, 0xbfb8aa3b, v149
	v_mul_f32_e32 v200, 0xbfb8aa3b, v150
	v_mul_f32_e32 v201, 0xbfb8aa3b, v151
	v_mul_f32_e32 v202, 0xbfb8aa3b, v152
	v_mul_f32_e32 v203, 0xbfb8aa3b, v153
	v_mul_f32_e32 v204, 0xbfb8aa3b, v154
	v_mul_f32_e32 v205, 0xbfb8aa3b, v155
	v_exp_f32_e32 v180, v180
	v_exp_f32_e32 v181, v181
	v_exp_f32_e32 v182, v182
	v_exp_f32_e32 v183, v183
	v_exp_f32_e32 v184, v184
	v_exp_f32_e32 v185, v185
	v_exp_f32_e32 v186, v186
	v_exp_f32_e32 v187, v187
	v_exp_f32_e32 v198, v198
	v_exp_f32_e32 v199, v199
	v_exp_f32_e32 v200, v200
	v_exp_f32_e32 v201, v201
	v_exp_f32_e32 v202, v202
	v_exp_f32_e32 v203, v203
	v_exp_f32_e32 v204, v204
	v_exp_f32_e32 v205, v205
	v_mul_f32_e32 v24, v24, v172
	v_mul_f32_e32 v25, v25, v172
	v_mul_f32_e32 v26, v26, v172
	v_mul_f32_e32 v27, v27, v172
	v_mul_f32_e32 v28, v28, v172
	v_mul_f32_e32 v29, v29, v172
	v_mul_f32_e32 v30, v30, v172
	v_mul_f32_e32 v31, v31, v172
	v_mul_f32_e32 v32, v32, v172
	v_mul_f32_e32 v33, v33, v172
	v_mul_f32_e32 v34, v34, v172
	v_mul_f32_e32 v35, v35, v172
	v_mul_f32_e32 v36, v36, v172
	v_mul_f32_e32 v37, v37, v172
	v_mul_f32_e32 v38, v38, v172
	v_mul_f32_e32 v39, v39, v172
	v_add_f32_e32 v180, 1.0, v180
	v_add_f32_e32 v181, 1.0, v181
	v_add_f32_e32 v182, 1.0, v182
	v_add_f32_e32 v183, 1.0, v183
	v_add_f32_e32 v184, 1.0, v184
	v_add_f32_e32 v185, 1.0, v185
	v_add_f32_e32 v186, 1.0, v186
	v_add_f32_e32 v187, 1.0, v187
	v_add_f32_e32 v198, 1.0, v198
	v_add_f32_e32 v199, 1.0, v199
	v_add_f32_e32 v200, 1.0, v200
	v_add_f32_e32 v201, 1.0, v201
	v_add_f32_e32 v202, 1.0, v202
	v_add_f32_e32 v203, 1.0, v203
	v_add_f32_e32 v204, 1.0, v204
	v_add_f32_e32 v205, 1.0, v205
	v_rcp_f32_e32 v180, v180
	v_rcp_f32_e32 v181, v181
	v_rcp_f32_e32 v182, v182
	v_rcp_f32_e32 v183, v183
	v_rcp_f32_e32 v184, v184
	v_rcp_f32_e32 v185, v185
	v_rcp_f32_e32 v186, v186
	v_rcp_f32_e32 v187, v187
	v_rcp_f32_e32 v198, v198
	v_rcp_f32_e32 v199, v199
	v_rcp_f32_e32 v200, v200
	v_rcp_f32_e32 v201, v201
	v_rcp_f32_e32 v202, v202
	v_rcp_f32_e32 v203, v203
	v_rcp_f32_e32 v204, v204
	v_rcp_f32_e32 v205, v205
	v_mul_f32_e32 v24, v24, v140
	v_mul_f32_e32 v25, v25, v141
	v_mul_f32_e32 v26, v26, v142
	v_mul_f32_e32 v27, v27, v143
	v_mul_f32_e32 v28, v28, v144
	v_mul_f32_e32 v29, v29, v145
	v_mul_f32_e32 v30, v30, v146
	v_mul_f32_e32 v31, v31, v147
	v_mul_f32_e32 v32, v32, v148
	v_mul_f32_e32 v33, v33, v149
	v_mul_f32_e32 v34, v34, v150
	v_mul_f32_e32 v35, v35, v151
	v_mul_f32_e32 v36, v36, v152
	v_mul_f32_e32 v37, v37, v153
	v_mul_f32_e32 v38, v38, v154
	v_mul_f32_e32 v39, v39, v155
	v_mul_f32_e32 v24, v24, v180
	v_mul_f32_e32 v25, v25, v181
	v_mul_f32_e32 v26, v26, v182
	v_mul_f32_e32 v27, v27, v183
	v_mul_f32_e32 v28, v28, v184
	v_mul_f32_e32 v29, v29, v185
	v_mul_f32_e32 v30, v30, v186
	v_mul_f32_e32 v31, v31, v187
	v_mul_f32_e32 v32, v32, v198
	v_mul_f32_e32 v33, v33, v199
	v_mul_f32_e32 v34, v34, v200
	v_mul_f32_e32 v35, v35, v201
	v_mul_f32_e32 v36, v36, v202
	v_mul_f32_e32 v37, v37, v203
	v_mul_f32_e32 v38, v38, v204
	v_mul_f32_e32 v39, v39, v205
	v_cvt_pk_bf16_f32 v164, v24, v25
	v_cvt_pk_bf16_f32 v165, v26, v27
	v_cvt_pk_bf16_f32 v166, v28, v29
	v_cvt_pk_bf16_f32 v167, v30, v31
	v_cvt_pk_bf16_f32 v168, v32, v33
	v_cvt_pk_bf16_f32 v169, v34, v35
	v_cvt_pk_bf16_f32 v170, v36, v37
	v_cvt_pk_bf16_f32 v171, v38, v39
	s_add_i32 s5, s41, s54
	s_add_i32 s5, s5, 2
	s_lshl_b32 s5, s5, 17
	s_add_u32 s0, s58, s5
	s_addc_u32 s1, s59, 0
	global_store_dwordx4 v196, v[164:167], s[0:1]
	global_store_dwordx4 v196, v[168:171], s[0:1] offset:16
	s_nop 1
	s_waitcnt vmcnt(12)
	v_rcp_f32_e32 v172, v80
	v_lshlrev_b32_e32 v140, 16, v124
	v_and_b32_e32 v141, 0xffff0000, v124
	v_lshlrev_b32_e32 v142, 16, v125
	v_and_b32_e32 v143, 0xffff0000, v125
	v_lshlrev_b32_e32 v144, 16, v126
	v_and_b32_e32 v145, 0xffff0000, v126
	v_lshlrev_b32_e32 v146, 16, v127
	v_and_b32_e32 v147, 0xffff0000, v127
	v_lshlrev_b32_e32 v148, 16, v128
	v_and_b32_e32 v149, 0xffff0000, v128
	v_lshlrev_b32_e32 v150, 16, v129
	v_and_b32_e32 v151, 0xffff0000, v129
	v_lshlrev_b32_e32 v152, 16, v130
	v_and_b32_e32 v153, 0xffff0000, v130
	v_lshlrev_b32_e32 v154, 16, v131
	v_and_b32_e32 v155, 0xffff0000, v131
	v_mul_f32_e32 v180, 0xbfb8aa3b, v140
	v_mul_f32_e32 v181, 0xbfb8aa3b, v141
	v_mul_f32_e32 v182, 0xbfb8aa3b, v142
	v_mul_f32_e32 v183, 0xbfb8aa3b, v143
	v_mul_f32_e32 v184, 0xbfb8aa3b, v144
	v_mul_f32_e32 v185, 0xbfb8aa3b, v145
	v_mul_f32_e32 v186, 0xbfb8aa3b, v146
	v_mul_f32_e32 v187, 0xbfb8aa3b, v147
	v_mul_f32_e32 v198, 0xbfb8aa3b, v148
	v_mul_f32_e32 v199, 0xbfb8aa3b, v149
	v_mul_f32_e32 v200, 0xbfb8aa3b, v150
	v_mul_f32_e32 v201, 0xbfb8aa3b, v151
	v_mul_f32_e32 v202, 0xbfb8aa3b, v152
	v_mul_f32_e32 v203, 0xbfb8aa3b, v153
	v_mul_f32_e32 v204, 0xbfb8aa3b, v154
	v_mul_f32_e32 v205, 0xbfb8aa3b, v155
	v_exp_f32_e32 v180, v180
	v_exp_f32_e32 v181, v181
	v_exp_f32_e32 v182, v182
	v_exp_f32_e32 v183, v183
	v_exp_f32_e32 v184, v184
	v_exp_f32_e32 v185, v185
	v_exp_f32_e32 v186, v186
	v_exp_f32_e32 v187, v187
	v_exp_f32_e32 v198, v198
	v_exp_f32_e32 v199, v199
	v_exp_f32_e32 v200, v200
	v_exp_f32_e32 v201, v201
	v_exp_f32_e32 v202, v202
	v_exp_f32_e32 v203, v203
	v_exp_f32_e32 v204, v204
	v_exp_f32_e32 v205, v205
	v_mul_f32_e32 v40, v40, v172
	v_mul_f32_e32 v41, v41, v172
	v_mul_f32_e32 v42, v42, v172
	v_mul_f32_e32 v43, v43, v172
	v_mul_f32_e32 v44, v44, v172
	v_mul_f32_e32 v45, v45, v172
	v_mul_f32_e32 v46, v46, v172
	v_mul_f32_e32 v47, v47, v172
	v_mul_f32_e32 v48, v48, v172
	v_mul_f32_e32 v49, v49, v172
	v_mul_f32_e32 v50, v50, v172
	v_mul_f32_e32 v51, v51, v172
	v_mul_f32_e32 v52, v52, v172
	v_mul_f32_e32 v53, v53, v172
	v_mul_f32_e32 v54, v54, v172
	v_mul_f32_e32 v55, v55, v172
	v_add_f32_e32 v180, 1.0, v180
	v_add_f32_e32 v181, 1.0, v181
	v_add_f32_e32 v182, 1.0, v182
	v_add_f32_e32 v183, 1.0, v183
	v_add_f32_e32 v184, 1.0, v184
	v_add_f32_e32 v185, 1.0, v185
	v_add_f32_e32 v186, 1.0, v186
	v_add_f32_e32 v187, 1.0, v187
	v_add_f32_e32 v198, 1.0, v198
	v_add_f32_e32 v199, 1.0, v199
	v_add_f32_e32 v200, 1.0, v200
	v_add_f32_e32 v201, 1.0, v201
	v_add_f32_e32 v202, 1.0, v202
	v_add_f32_e32 v203, 1.0, v203
	v_add_f32_e32 v204, 1.0, v204
	v_add_f32_e32 v205, 1.0, v205
	v_rcp_f32_e32 v180, v180
	v_rcp_f32_e32 v181, v181
	v_rcp_f32_e32 v182, v182
	v_rcp_f32_e32 v183, v183
	v_rcp_f32_e32 v184, v184
	v_rcp_f32_e32 v185, v185
	v_rcp_f32_e32 v186, v186
	v_rcp_f32_e32 v187, v187
	v_rcp_f32_e32 v198, v198
	v_rcp_f32_e32 v199, v199
	v_rcp_f32_e32 v200, v200
	v_rcp_f32_e32 v201, v201
	v_rcp_f32_e32 v202, v202
	v_rcp_f32_e32 v203, v203
	v_rcp_f32_e32 v204, v204
	v_rcp_f32_e32 v205, v205
	v_mul_f32_e32 v40, v40, v140
	v_mul_f32_e32 v41, v41, v141
	v_mul_f32_e32 v42, v42, v142
	v_mul_f32_e32 v43, v43, v143
	v_mul_f32_e32 v44, v44, v144
	v_mul_f32_e32 v45, v45, v145
	v_mul_f32_e32 v46, v46, v146
	v_mul_f32_e32 v47, v47, v147
	v_mul_f32_e32 v48, v48, v148
	v_mul_f32_e32 v49, v49, v149
	v_mul_f32_e32 v50, v50, v150
	v_mul_f32_e32 v51, v51, v151
	v_mul_f32_e32 v52, v52, v152
	v_mul_f32_e32 v53, v53, v153
	v_mul_f32_e32 v54, v54, v154
	v_mul_f32_e32 v55, v55, v155
	v_mul_f32_e32 v40, v40, v180
	v_mul_f32_e32 v41, v41, v181
	v_mul_f32_e32 v42, v42, v182
	v_mul_f32_e32 v43, v43, v183
	v_mul_f32_e32 v44, v44, v184
	v_mul_f32_e32 v45, v45, v185
	v_mul_f32_e32 v46, v46, v186
	v_mul_f32_e32 v47, v47, v187
	v_mul_f32_e32 v48, v48, v198
	v_mul_f32_e32 v49, v49, v199
	v_mul_f32_e32 v50, v50, v200
	v_mul_f32_e32 v51, v51, v201
	v_mul_f32_e32 v52, v52, v202
	v_mul_f32_e32 v53, v53, v203
	v_mul_f32_e32 v54, v54, v204
	v_mul_f32_e32 v55, v55, v205
	v_cvt_pk_bf16_f32 v164, v40, v41
	v_cvt_pk_bf16_f32 v165, v42, v43
	v_cvt_pk_bf16_f32 v166, v44, v45
	v_cvt_pk_bf16_f32 v167, v46, v47
	v_cvt_pk_bf16_f32 v168, v48, v49
	v_cvt_pk_bf16_f32 v169, v50, v51
	v_cvt_pk_bf16_f32 v170, v52, v53
	v_cvt_pk_bf16_f32 v171, v54, v55
	s_add_i32 s5, s41, s54
	s_add_i32 s5, s5, 4
	s_lshl_b32 s5, s5, 17
	s_add_u32 s0, s58, s5
	s_addc_u32 s1, s59, 0
	global_store_dwordx4 v196, v[164:167], s[0:1]
	global_store_dwordx4 v196, v[168:171], s[0:1] offset:16
	s_nop 1
	v_rcp_f32_e32 v172, v84
	v_lshlrev_b32_e32 v140, 16, v132
	v_and_b32_e32 v141, 0xffff0000, v132
	v_lshlrev_b32_e32 v142, 16, v133
	v_and_b32_e32 v143, 0xffff0000, v133
	v_lshlrev_b32_e32 v144, 16, v134
	v_and_b32_e32 v145, 0xffff0000, v134
	v_lshlrev_b32_e32 v146, 16, v135
	v_and_b32_e32 v147, 0xffff0000, v135
	v_lshlrev_b32_e32 v148, 16, v136
	v_and_b32_e32 v149, 0xffff0000, v136
	v_lshlrev_b32_e32 v150, 16, v137
	v_and_b32_e32 v151, 0xffff0000, v137
	v_lshlrev_b32_e32 v152, 16, v138
	v_and_b32_e32 v153, 0xffff0000, v138
	v_lshlrev_b32_e32 v154, 16, v139
	v_and_b32_e32 v155, 0xffff0000, v139
	v_mul_f32_e32 v180, 0xbfb8aa3b, v140
	v_mul_f32_e32 v181, 0xbfb8aa3b, v141
	v_mul_f32_e32 v182, 0xbfb8aa3b, v142
	v_mul_f32_e32 v183, 0xbfb8aa3b, v143
	v_mul_f32_e32 v184, 0xbfb8aa3b, v144
	v_mul_f32_e32 v185, 0xbfb8aa3b, v145
	v_mul_f32_e32 v186, 0xbfb8aa3b, v146
	v_mul_f32_e32 v187, 0xbfb8aa3b, v147
	v_mul_f32_e32 v198, 0xbfb8aa3b, v148
	v_mul_f32_e32 v199, 0xbfb8aa3b, v149
	v_mul_f32_e32 v200, 0xbfb8aa3b, v150
	v_mul_f32_e32 v201, 0xbfb8aa3b, v151
	v_mul_f32_e32 v202, 0xbfb8aa3b, v152
	v_mul_f32_e32 v203, 0xbfb8aa3b, v153
	v_mul_f32_e32 v204, 0xbfb8aa3b, v154
	v_mul_f32_e32 v205, 0xbfb8aa3b, v155
	v_exp_f32_e32 v180, v180
	v_exp_f32_e32 v181, v181
	v_exp_f32_e32 v182, v182
	v_exp_f32_e32 v183, v183
	v_exp_f32_e32 v184, v184
	v_exp_f32_e32 v185, v185
	v_exp_f32_e32 v186, v186
	v_exp_f32_e32 v187, v187
	v_exp_f32_e32 v198, v198
	v_exp_f32_e32 v199, v199
	v_exp_f32_e32 v200, v200
	v_exp_f32_e32 v201, v201
	v_exp_f32_e32 v202, v202
	v_exp_f32_e32 v203, v203
	v_exp_f32_e32 v204, v204
	v_exp_f32_e32 v205, v205
	v_mul_f32_e32 v56, v56, v172
	v_mul_f32_e32 v57, v57, v172
	v_mul_f32_e32 v58, v58, v172
	v_mul_f32_e32 v59, v59, v172
	v_mul_f32_e32 v60, v60, v172
	v_mul_f32_e32 v61, v61, v172
	v_mul_f32_e32 v62, v62, v172
	v_mul_f32_e32 v63, v63, v172
	v_mul_f32_e32 v64, v64, v172
	v_mul_f32_e32 v65, v65, v172
	v_mul_f32_e32 v66, v66, v172
	v_mul_f32_e32 v67, v67, v172
	v_mul_f32_e32 v68, v68, v172
	v_mul_f32_e32 v69, v69, v172
	v_mul_f32_e32 v70, v70, v172
	v_mul_f32_e32 v71, v71, v172
	v_add_f32_e32 v180, 1.0, v180
	v_add_f32_e32 v181, 1.0, v181
	v_add_f32_e32 v182, 1.0, v182
	v_add_f32_e32 v183, 1.0, v183
	v_add_f32_e32 v184, 1.0, v184
	v_add_f32_e32 v185, 1.0, v185
	v_add_f32_e32 v186, 1.0, v186
	v_add_f32_e32 v187, 1.0, v187
	v_add_f32_e32 v198, 1.0, v198
	v_add_f32_e32 v199, 1.0, v199
	v_add_f32_e32 v200, 1.0, v200
	v_add_f32_e32 v201, 1.0, v201
	v_add_f32_e32 v202, 1.0, v202
	v_add_f32_e32 v203, 1.0, v203
	v_add_f32_e32 v204, 1.0, v204
	v_add_f32_e32 v205, 1.0, v205
	v_rcp_f32_e32 v180, v180
	v_rcp_f32_e32 v181, v181
	v_rcp_f32_e32 v182, v182
	v_rcp_f32_e32 v183, v183
	v_rcp_f32_e32 v184, v184
	v_rcp_f32_e32 v185, v185
	v_rcp_f32_e32 v186, v186
	v_rcp_f32_e32 v187, v187
	v_rcp_f32_e32 v198, v198
	v_rcp_f32_e32 v199, v199
	v_rcp_f32_e32 v200, v200
	v_rcp_f32_e32 v201, v201
	v_rcp_f32_e32 v202, v202
	v_rcp_f32_e32 v203, v203
	v_rcp_f32_e32 v204, v204
	v_rcp_f32_e32 v205, v205
	v_mul_f32_e32 v56, v56, v140
	v_mul_f32_e32 v57, v57, v141
	v_mul_f32_e32 v58, v58, v142
	v_mul_f32_e32 v59, v59, v143
	v_mul_f32_e32 v60, v60, v144
	v_mul_f32_e32 v61, v61, v145
	v_mul_f32_e32 v62, v62, v146
	v_mul_f32_e32 v63, v63, v147
	v_mul_f32_e32 v64, v64, v148
	v_mul_f32_e32 v65, v65, v149
	v_mul_f32_e32 v66, v66, v150
	v_mul_f32_e32 v67, v67, v151
	v_mul_f32_e32 v68, v68, v152
	v_mul_f32_e32 v69, v69, v153
	v_mul_f32_e32 v70, v70, v154
	v_mul_f32_e32 v71, v71, v155
	v_mul_f32_e32 v56, v56, v180
	v_mul_f32_e32 v57, v57, v181
	v_mul_f32_e32 v58, v58, v182
	v_mul_f32_e32 v59, v59, v183
	v_mul_f32_e32 v60, v60, v184
	v_mul_f32_e32 v61, v61, v185
	v_mul_f32_e32 v62, v62, v186
	v_mul_f32_e32 v63, v63, v187
	v_mul_f32_e32 v64, v64, v198
	v_mul_f32_e32 v65, v65, v199
	v_mul_f32_e32 v66, v66, v200
	v_mul_f32_e32 v67, v67, v201
	v_mul_f32_e32 v68, v68, v202
	v_mul_f32_e32 v69, v69, v203
	v_mul_f32_e32 v70, v70, v204
	v_mul_f32_e32 v71, v71, v205
	v_cvt_pk_bf16_f32 v164, v56, v57
	v_cvt_pk_bf16_f32 v165, v58, v59
	v_cvt_pk_bf16_f32 v166, v60, v61
	v_cvt_pk_bf16_f32 v167, v62, v63
	v_cvt_pk_bf16_f32 v168, v64, v65
	v_cvt_pk_bf16_f32 v169, v66, v67
	v_cvt_pk_bf16_f32 v170, v68, v69
	v_cvt_pk_bf16_f32 v171, v70, v71
	s_add_i32 s5, s41, s54
	s_add_i32 s5, s5, 6
	s_lshl_b32 s5, s5, 17
	s_add_u32 s0, s58, s5
	s_addc_u32 s1, s59, 0
	global_store_dwordx4 v196, v[164:167], s[0:1]
	global_store_dwordx4 v196, v[168:171], s[0:1] offset:16
	s_nop 1
	s_add_i32 s63, s63, 1
	s_add_i32 s41, s41, 8
	s_add_i32 s42, s41, -4
	s_max_i32 s42, s42, 0
	s_min_i32 s42, s42, 0x78
	s_add_i32 s43, s41, 3
	s_max_i32 s43, s43, 0
	s_min_i32 s43, s43, 0x78
	s_add_i32 s43, s43, 7
	s_sub_i32 s45, s43, s42
	s_add_i32 s45, s45, 2
	s_lshr_b32 s45, s45, 1
	s_add_i32 s47, s41, s54
	s_add_i32 s47, s47, -4
	s_max_i32 s47, s47, 0
	s_min_i32 s47, s47, 0x78
	s_add_i32 s48, s41, s54
	s_add_i32 s48, s48, -2
	s_max_i32 s48, s48, 0
	s_min_i32 s48, s48, 0x78
	s_add_i32 s49, s41, s54
	s_add_i32 s49, s49, 0
	s_max_i32 s49, s49, 0
	s_min_i32 s49, s49, 0x78
	s_add_i32 s50, s41, s54
	s_add_i32 s50, s50, 2
	s_max_i32 s50, s50, 0
	s_min_i32 s50, s50, 0x78
	s_branch .La0_round
.La0_last_round:
	s_waitcnt vmcnt(4)
	v_rcp_f32_e32 v172, v72
	v_lshlrev_b32_e32 v140, 16, v210
	v_and_b32_e32 v141, 0xffff0000, v210
	v_lshlrev_b32_e32 v142, 16, v211
	v_and_b32_e32 v143, 0xffff0000, v211
	v_lshlrev_b32_e32 v144, 16, v212
	v_and_b32_e32 v145, 0xffff0000, v212
	v_lshlrev_b32_e32 v146, 16, v213
	v_and_b32_e32 v147, 0xffff0000, v213
	v_lshlrev_b32_e32 v148, 16, v214
	v_and_b32_e32 v149, 0xffff0000, v214
	v_lshlrev_b32_e32 v150, 16, v215
	v_and_b32_e32 v151, 0xffff0000, v215
	v_lshlrev_b32_e32 v152, 16, v216
	v_and_b32_e32 v153, 0xffff0000, v216
	v_lshlrev_b32_e32 v154, 16, v217
	v_and_b32_e32 v155, 0xffff0000, v217
	v_mul_f32_e32 v180, 0xbfb8aa3b, v140
	v_mul_f32_e32 v181, 0xbfb8aa3b, v141
	v_mul_f32_e32 v182, 0xbfb8aa3b, v142
	v_mul_f32_e32 v183, 0xbfb8aa3b, v143
	v_mul_f32_e32 v184, 0xbfb8aa3b, v144
	v_mul_f32_e32 v185, 0xbfb8aa3b, v145
	v_mul_f32_e32 v186, 0xbfb8aa3b, v146
	v_mul_f32_e32 v187, 0xbfb8aa3b, v147
	v_mul_f32_e32 v198, 0xbfb8aa3b, v148
	v_mul_f32_e32 v199, 0xbfb8aa3b, v149
	v_mul_f32_e32 v200, 0xbfb8aa3b, v150
	v_mul_f32_e32 v201, 0xbfb8aa3b, v151
	v_mul_f32_e32 v202, 0xbfb8aa3b, v152
	v_mul_f32_e32 v203, 0xbfb8aa3b, v153
	v_mul_f32_e32 v204, 0xbfb8aa3b, v154
	v_mul_f32_e32 v205, 0xbfb8aa3b, v155
	v_exp_f32_e32 v180, v180
	v_exp_f32_e32 v181, v181
	v_exp_f32_e32 v182, v182
	v_exp_f32_e32 v183, v183
	v_exp_f32_e32 v184, v184
	v_exp_f32_e32 v185, v185
	v_exp_f32_e32 v186, v186
	v_exp_f32_e32 v187, v187
	v_exp_f32_e32 v198, v198
	v_exp_f32_e32 v199, v199
	v_exp_f32_e32 v200, v200
	v_exp_f32_e32 v201, v201
	v_exp_f32_e32 v202, v202
	v_exp_f32_e32 v203, v203
	v_exp_f32_e32 v204, v204
	v_exp_f32_e32 v205, v205
	v_mul_f32_e32 v8, v8, v172
	v_mul_f32_e32 v9, v9, v172
	v_mul_f32_e32 v10, v10, v172
	v_mul_f32_e32 v11, v11, v172
	v_mul_f32_e32 v12, v12, v172
	v_mul_f32_e32 v13, v13, v172
	v_mul_f32_e32 v14, v14, v172
	v_mul_f32_e32 v15, v15, v172
	v_mul_f32_e32 v16, v16, v172
	v_mul_f32_e32 v17, v17, v172
	v_mul_f32_e32 v18, v18, v172
	v_mul_f32_e32 v19, v19, v172
	v_mul_f32_e32 v20, v20, v172
	v_mul_f32_e32 v21, v21, v172
	v_mul_f32_e32 v22, v22, v172
	v_mul_f32_e32 v23, v23, v172
	v_add_f32_e32 v180, 1.0, v180
	v_add_f32_e32 v181, 1.0, v181
	v_add_f32_e32 v182, 1.0, v182
	v_add_f32_e32 v183, 1.0, v183
	v_add_f32_e32 v184, 1.0, v184
	v_add_f32_e32 v185, 1.0, v185
	v_add_f32_e32 v186, 1.0, v186
	v_add_f32_e32 v187, 1.0, v187
	v_add_f32_e32 v198, 1.0, v198
	v_add_f32_e32 v199, 1.0, v199
	v_add_f32_e32 v200, 1.0, v200
	v_add_f32_e32 v201, 1.0, v201
	v_add_f32_e32 v202, 1.0, v202
	v_add_f32_e32 v203, 1.0, v203
	v_add_f32_e32 v204, 1.0, v204
	v_add_f32_e32 v205, 1.0, v205
	v_rcp_f32_e32 v180, v180
	v_rcp_f32_e32 v181, v181
	v_rcp_f32_e32 v182, v182
	v_rcp_f32_e32 v183, v183
	v_rcp_f32_e32 v184, v184
	v_rcp_f32_e32 v185, v185
	v_rcp_f32_e32 v186, v186
	v_rcp_f32_e32 v187, v187
	v_rcp_f32_e32 v198, v198
	v_rcp_f32_e32 v199, v199
	v_rcp_f32_e32 v200, v200
	v_rcp_f32_e32 v201, v201
	v_rcp_f32_e32 v202, v202
	v_rcp_f32_e32 v203, v203
	v_rcp_f32_e32 v204, v204
	v_rcp_f32_e32 v205, v205
	v_mul_f32_e32 v8, v8, v140
	v_mul_f32_e32 v9, v9, v141
	v_mul_f32_e32 v10, v10, v142
	v_mul_f32_e32 v11, v11, v143
	v_mul_f32_e32 v12, v12, v144
	v_mul_f32_e32 v13, v13, v145
	v_mul_f32_e32 v14, v14, v146
	v_mul_f32_e32 v15, v15, v147
	v_mul_f32_e32 v16, v16, v148
	v_mul_f32_e32 v17, v17, v149
	v_mul_f32_e32 v18, v18, v150
	v_mul_f32_e32 v19, v19, v151
	v_mul_f32_e32 v20, v20, v152
	v_mul_f32_e32 v21, v21, v153
	v_mul_f32_e32 v22, v22, v154
	v_mul_f32_e32 v23, v23, v155
	v_mul_f32_e32 v8, v8, v180
	v_mul_f32_e32 v9, v9, v181
	v_mul_f32_e32 v10, v10, v182
	v_mul_f32_e32 v11, v11, v183
	v_mul_f32_e32 v12, v12, v184
	v_mul_f32_e32 v13, v13, v185
	v_mul_f32_e32 v14, v14, v186
	v_mul_f32_e32 v15, v15, v187
	v_mul_f32_e32 v16, v16, v198
	v_mul_f32_e32 v17, v17, v199
	v_mul_f32_e32 v18, v18, v200
	v_mul_f32_e32 v19, v19, v201
	v_mul_f32_e32 v20, v20, v202
	v_mul_f32_e32 v21, v21, v203
	v_mul_f32_e32 v22, v22, v204
	v_mul_f32_e32 v23, v23, v205
	v_cvt_pk_bf16_f32 v164, v8, v9
	v_cvt_pk_bf16_f32 v165, v10, v11
	v_cvt_pk_bf16_f32 v166, v12, v13
	v_cvt_pk_bf16_f32 v167, v14, v15
	v_cvt_pk_bf16_f32 v168, v16, v17
	v_cvt_pk_bf16_f32 v169, v18, v19
	v_cvt_pk_bf16_f32 v170, v20, v21
	v_cvt_pk_bf16_f32 v171, v22, v23
	s_add_i32 s5, s41, s54
	s_add_i32 s5, s5, 0
	s_lshl_b32 s5, s5, 17
	s_add_u32 s0, s58, s5
	s_addc_u32 s1, s59, 0
	global_store_dwordx4 v196, v[164:167], s[0:1]
	global_store_dwordx4 v196, v[168:171], s[0:1] offset:16
	s_nop 1
	v_rcp_f32_e32 v172, v76
	v_lshlrev_b32_e32 v140, 16, v218
	v_and_b32_e32 v141, 0xffff0000, v218
	v_lshlrev_b32_e32 v142, 16, v219
	v_and_b32_e32 v143, 0xffff0000, v219
	v_lshlrev_b32_e32 v144, 16, v220
	v_and_b32_e32 v145, 0xffff0000, v220
	v_lshlrev_b32_e32 v146, 16, v221
	v_and_b32_e32 v147, 0xffff0000, v221
	v_lshlrev_b32_e32 v148, 16, v222
	v_and_b32_e32 v149, 0xffff0000, v222
	v_lshlrev_b32_e32 v150, 16, v223
	v_and_b32_e32 v151, 0xffff0000, v223
	v_lshlrev_b32_e32 v152, 16, v224
	v_and_b32_e32 v153, 0xffff0000, v224
	v_lshlrev_b32_e32 v154, 16, v225
	v_and_b32_e32 v155, 0xffff0000, v225
	v_mul_f32_e32 v180, 0xbfb8aa3b, v140
	v_mul_f32_e32 v181, 0xbfb8aa3b, v141
	v_mul_f32_e32 v182, 0xbfb8aa3b, v142
	v_mul_f32_e32 v183, 0xbfb8aa3b, v143
	v_mul_f32_e32 v184, 0xbfb8aa3b, v144
	v_mul_f32_e32 v185, 0xbfb8aa3b, v145
	v_mul_f32_e32 v186, 0xbfb8aa3b, v146
	v_mul_f32_e32 v187, 0xbfb8aa3b, v147
	v_mul_f32_e32 v198, 0xbfb8aa3b, v148
	v_mul_f32_e32 v199, 0xbfb8aa3b, v149
	v_mul_f32_e32 v200, 0xbfb8aa3b, v150
	v_mul_f32_e32 v201, 0xbfb8aa3b, v151
	v_mul_f32_e32 v202, 0xbfb8aa3b, v152
	v_mul_f32_e32 v203, 0xbfb8aa3b, v153
	v_mul_f32_e32 v204, 0xbfb8aa3b, v154
	v_mul_f32_e32 v205, 0xbfb8aa3b, v155
	v_exp_f32_e32 v180, v180
	v_exp_f32_e32 v181, v181
	v_exp_f32_e32 v182, v182
	v_exp_f32_e32 v183, v183
	v_exp_f32_e32 v184, v184
	v_exp_f32_e32 v185, v185
	v_exp_f32_e32 v186, v186
	v_exp_f32_e32 v187, v187
	v_exp_f32_e32 v198, v198
	v_exp_f32_e32 v199, v199
	v_exp_f32_e32 v200, v200
	v_exp_f32_e32 v201, v201
	v_exp_f32_e32 v202, v202
	v_exp_f32_e32 v203, v203
	v_exp_f32_e32 v204, v204
	v_exp_f32_e32 v205, v205
	v_mul_f32_e32 v24, v24, v172
	v_mul_f32_e32 v25, v25, v172
	v_mul_f32_e32 v26, v26, v172
	v_mul_f32_e32 v27, v27, v172
	v_mul_f32_e32 v28, v28, v172
	v_mul_f32_e32 v29, v29, v172
	v_mul_f32_e32 v30, v30, v172
	v_mul_f32_e32 v31, v31, v172
	v_mul_f32_e32 v32, v32, v172
	v_mul_f32_e32 v33, v33, v172
	v_mul_f32_e32 v34, v34, v172
	v_mul_f32_e32 v35, v35, v172
	v_mul_f32_e32 v36, v36, v172
	v_mul_f32_e32 v37, v37, v172
	v_mul_f32_e32 v38, v38, v172
	v_mul_f32_e32 v39, v39, v172
	v_add_f32_e32 v180, 1.0, v180
	v_add_f32_e32 v181, 1.0, v181
	v_add_f32_e32 v182, 1.0, v182
	v_add_f32_e32 v183, 1.0, v183
	v_add_f32_e32 v184, 1.0, v184
	v_add_f32_e32 v185, 1.0, v185
	v_add_f32_e32 v186, 1.0, v186
	v_add_f32_e32 v187, 1.0, v187
	v_add_f32_e32 v198, 1.0, v198
	v_add_f32_e32 v199, 1.0, v199
	v_add_f32_e32 v200, 1.0, v200
	v_add_f32_e32 v201, 1.0, v201
	v_add_f32_e32 v202, 1.0, v202
	v_add_f32_e32 v203, 1.0, v203
	v_add_f32_e32 v204, 1.0, v204
	v_add_f32_e32 v205, 1.0, v205
	v_rcp_f32_e32 v180, v180
	v_rcp_f32_e32 v181, v181
	v_rcp_f32_e32 v182, v182
	v_rcp_f32_e32 v183, v183
	v_rcp_f32_e32 v184, v184
	v_rcp_f32_e32 v185, v185
	v_rcp_f32_e32 v186, v186
	v_rcp_f32_e32 v187, v187
	v_rcp_f32_e32 v198, v198
	v_rcp_f32_e32 v199, v199
	v_rcp_f32_e32 v200, v200
	v_rcp_f32_e32 v201, v201
	v_rcp_f32_e32 v202, v202
	v_rcp_f32_e32 v203, v203
	v_rcp_f32_e32 v204, v204
	v_rcp_f32_e32 v205, v205
	v_mul_f32_e32 v24, v24, v140
	v_mul_f32_e32 v25, v25, v141
	v_mul_f32_e32 v26, v26, v142
	v_mul_f32_e32 v27, v27, v143
	v_mul_f32_e32 v28, v28, v144
	v_mul_f32_e32 v29, v29, v145
	v_mul_f32_e32 v30, v30, v146
	v_mul_f32_e32 v31, v31, v147
	v_mul_f32_e32 v32, v32, v148
	v_mul_f32_e32 v33, v33, v149
	v_mul_f32_e32 v34, v34, v150
	v_mul_f32_e32 v35, v35, v151
	v_mul_f32_e32 v36, v36, v152
	v_mul_f32_e32 v37, v37, v153
	v_mul_f32_e32 v38, v38, v154
	v_mul_f32_e32 v39, v39, v155
	v_mul_f32_e32 v24, v24, v180
	v_mul_f32_e32 v25, v25, v181
	v_mul_f32_e32 v26, v26, v182
	v_mul_f32_e32 v27, v27, v183
	v_mul_f32_e32 v28, v28, v184
	v_mul_f32_e32 v29, v29, v185
	v_mul_f32_e32 v30, v30, v186
	v_mul_f32_e32 v31, v31, v187
	v_mul_f32_e32 v32, v32, v198
	v_mul_f32_e32 v33, v33, v199
	v_mul_f32_e32 v34, v34, v200
	v_mul_f32_e32 v35, v35, v201
	v_mul_f32_e32 v36, v36, v202
	v_mul_f32_e32 v37, v37, v203
	v_mul_f32_e32 v38, v38, v204
	v_mul_f32_e32 v39, v39, v205
	v_cvt_pk_bf16_f32 v164, v24, v25
	v_cvt_pk_bf16_f32 v165, v26, v27
	v_cvt_pk_bf16_f32 v166, v28, v29
	v_cvt_pk_bf16_f32 v167, v30, v31
	v_cvt_pk_bf16_f32 v168, v32, v33
	v_cvt_pk_bf16_f32 v169, v34, v35
	v_cvt_pk_bf16_f32 v170, v36, v37
	v_cvt_pk_bf16_f32 v171, v38, v39
	s_add_i32 s5, s41, s54
	s_add_i32 s5, s5, 2
	s_lshl_b32 s5, s5, 17
	s_add_u32 s0, s58, s5
	s_addc_u32 s1, s59, 0
	global_store_dwordx4 v196, v[164:167], s[0:1]
	global_store_dwordx4 v196, v[168:171], s[0:1] offset:16
	s_nop 1
	s_waitcnt vmcnt(4)
	v_rcp_f32_e32 v172, v80
	v_lshlrev_b32_e32 v140, 16, v124
	v_and_b32_e32 v141, 0xffff0000, v124
	v_lshlrev_b32_e32 v142, 16, v125
	v_and_b32_e32 v143, 0xffff0000, v125
	v_lshlrev_b32_e32 v144, 16, v126
	v_and_b32_e32 v145, 0xffff0000, v126
	v_lshlrev_b32_e32 v146, 16, v127
	v_and_b32_e32 v147, 0xffff0000, v127
	v_lshlrev_b32_e32 v148, 16, v128
	v_and_b32_e32 v149, 0xffff0000, v128
	v_lshlrev_b32_e32 v150, 16, v129
	v_and_b32_e32 v151, 0xffff0000, v129
	v_lshlrev_b32_e32 v152, 16, v130
	v_and_b32_e32 v153, 0xffff0000, v130
	v_lshlrev_b32_e32 v154, 16, v131
	v_and_b32_e32 v155, 0xffff0000, v131
	v_mul_f32_e32 v180, 0xbfb8aa3b, v140
	v_mul_f32_e32 v181, 0xbfb8aa3b, v141
	v_mul_f32_e32 v182, 0xbfb8aa3b, v142
	v_mul_f32_e32 v183, 0xbfb8aa3b, v143
	v_mul_f32_e32 v184, 0xbfb8aa3b, v144
	v_mul_f32_e32 v185, 0xbfb8aa3b, v145
	v_mul_f32_e32 v186, 0xbfb8aa3b, v146
	v_mul_f32_e32 v187, 0xbfb8aa3b, v147
	v_mul_f32_e32 v198, 0xbfb8aa3b, v148
	v_mul_f32_e32 v199, 0xbfb8aa3b, v149
	v_mul_f32_e32 v200, 0xbfb8aa3b, v150
	v_mul_f32_e32 v201, 0xbfb8aa3b, v151
	v_mul_f32_e32 v202, 0xbfb8aa3b, v152
	v_mul_f32_e32 v203, 0xbfb8aa3b, v153
	v_mul_f32_e32 v204, 0xbfb8aa3b, v154
	v_mul_f32_e32 v205, 0xbfb8aa3b, v155
	v_exp_f32_e32 v180, v180
	v_exp_f32_e32 v181, v181
	v_exp_f32_e32 v182, v182
	v_exp_f32_e32 v183, v183
	v_exp_f32_e32 v184, v184
	v_exp_f32_e32 v185, v185
	v_exp_f32_e32 v186, v186
	v_exp_f32_e32 v187, v187
	v_exp_f32_e32 v198, v198
	v_exp_f32_e32 v199, v199
	v_exp_f32_e32 v200, v200
	v_exp_f32_e32 v201, v201
	v_exp_f32_e32 v202, v202
	v_exp_f32_e32 v203, v203
	v_exp_f32_e32 v204, v204
	v_exp_f32_e32 v205, v205
	v_mul_f32_e32 v40, v40, v172
	v_mul_f32_e32 v41, v41, v172
	v_mul_f32_e32 v42, v42, v172
	v_mul_f32_e32 v43, v43, v172
	v_mul_f32_e32 v44, v44, v172
	v_mul_f32_e32 v45, v45, v172
	v_mul_f32_e32 v46, v46, v172
	v_mul_f32_e32 v47, v47, v172
	v_mul_f32_e32 v48, v48, v172
	v_mul_f32_e32 v49, v49, v172
	v_mul_f32_e32 v50, v50, v172
	v_mul_f32_e32 v51, v51, v172
	v_mul_f32_e32 v52, v52, v172
	v_mul_f32_e32 v53, v53, v172
	v_mul_f32_e32 v54, v54, v172
	v_mul_f32_e32 v55, v55, v172
	v_add_f32_e32 v180, 1.0, v180
	v_add_f32_e32 v181, 1.0, v181
	v_add_f32_e32 v182, 1.0, v182
	v_add_f32_e32 v183, 1.0, v183
	v_add_f32_e32 v184, 1.0, v184
	v_add_f32_e32 v185, 1.0, v185
	v_add_f32_e32 v186, 1.0, v186
	v_add_f32_e32 v187, 1.0, v187
	v_add_f32_e32 v198, 1.0, v198
	v_add_f32_e32 v199, 1.0, v199
	v_add_f32_e32 v200, 1.0, v200
	v_add_f32_e32 v201, 1.0, v201
	v_add_f32_e32 v202, 1.0, v202
	v_add_f32_e32 v203, 1.0, v203
	v_add_f32_e32 v204, 1.0, v204
	v_add_f32_e32 v205, 1.0, v205
	v_rcp_f32_e32 v180, v180
	v_rcp_f32_e32 v181, v181
	v_rcp_f32_e32 v182, v182
	v_rcp_f32_e32 v183, v183
	v_rcp_f32_e32 v184, v184
	v_rcp_f32_e32 v185, v185
	v_rcp_f32_e32 v186, v186
	v_rcp_f32_e32 v187, v187
	v_rcp_f32_e32 v198, v198
	v_rcp_f32_e32 v199, v199
	v_rcp_f32_e32 v200, v200
	v_rcp_f32_e32 v201, v201
	v_rcp_f32_e32 v202, v202
	v_rcp_f32_e32 v203, v203
	v_rcp_f32_e32 v204, v204
	v_rcp_f32_e32 v205, v205
	v_mul_f32_e32 v40, v40, v140
	v_mul_f32_e32 v41, v41, v141
	v_mul_f32_e32 v42, v42, v142
	v_mul_f32_e32 v43, v43, v143
	v_mul_f32_e32 v44, v44, v144
	v_mul_f32_e32 v45, v45, v145
	v_mul_f32_e32 v46, v46, v146
	v_mul_f32_e32 v47, v47, v147
	v_mul_f32_e32 v48, v48, v148
	v_mul_f32_e32 v49, v49, v149
	v_mul_f32_e32 v50, v50, v150
	v_mul_f32_e32 v51, v51, v151
	v_mul_f32_e32 v52, v52, v152
	v_mul_f32_e32 v53, v53, v153
	v_mul_f32_e32 v54, v54, v154
	v_mul_f32_e32 v55, v55, v155
	v_mul_f32_e32 v40, v40, v180
	v_mul_f32_e32 v41, v41, v181
	v_mul_f32_e32 v42, v42, v182
	v_mul_f32_e32 v43, v43, v183
	v_mul_f32_e32 v44, v44, v184
	v_mul_f32_e32 v45, v45, v185
	v_mul_f32_e32 v46, v46, v186
	v_mul_f32_e32 v47, v47, v187
	v_mul_f32_e32 v48, v48, v198
	v_mul_f32_e32 v49, v49, v199
	v_mul_f32_e32 v50, v50, v200
	v_mul_f32_e32 v51, v51, v201
	v_mul_f32_e32 v52, v52, v202
	v_mul_f32_e32 v53, v53, v203
	v_mul_f32_e32 v54, v54, v204
	v_mul_f32_e32 v55, v55, v205
	v_cvt_pk_bf16_f32 v164, v40, v41
	v_cvt_pk_bf16_f32 v165, v42, v43
	v_cvt_pk_bf16_f32 v166, v44, v45
	v_cvt_pk_bf16_f32 v167, v46, v47
	v_cvt_pk_bf16_f32 v168, v48, v49
	v_cvt_pk_bf16_f32 v169, v50, v51
	v_cvt_pk_bf16_f32 v170, v52, v53
	v_cvt_pk_bf16_f32 v171, v54, v55
	s_add_i32 s5, s41, s54
	s_add_i32 s5, s5, 4
	s_lshl_b32 s5, s5, 17
	s_add_u32 s0, s58, s5
	s_addc_u32 s1, s59, 0
	global_store_dwordx4 v196, v[164:167], s[0:1]
	global_store_dwordx4 v196, v[168:171], s[0:1] offset:16
	s_nop 1
	v_rcp_f32_e32 v172, v84
	v_lshlrev_b32_e32 v140, 16, v132
	v_and_b32_e32 v141, 0xffff0000, v132
	v_lshlrev_b32_e32 v142, 16, v133
	v_and_b32_e32 v143, 0xffff0000, v133
	v_lshlrev_b32_e32 v144, 16, v134
	v_and_b32_e32 v145, 0xffff0000, v134
	v_lshlrev_b32_e32 v146, 16, v135
	v_and_b32_e32 v147, 0xffff0000, v135
	v_lshlrev_b32_e32 v148, 16, v136
	v_and_b32_e32 v149, 0xffff0000, v136
	v_lshlrev_b32_e32 v150, 16, v137
	v_and_b32_e32 v151, 0xffff0000, v137
	v_lshlrev_b32_e32 v152, 16, v138
	v_and_b32_e32 v153, 0xffff0000, v138
	v_lshlrev_b32_e32 v154, 16, v139
	v_and_b32_e32 v155, 0xffff0000, v139
	v_mul_f32_e32 v180, 0xbfb8aa3b, v140
	v_mul_f32_e32 v181, 0xbfb8aa3b, v141
	v_mul_f32_e32 v182, 0xbfb8aa3b, v142
	v_mul_f32_e32 v183, 0xbfb8aa3b, v143
	v_mul_f32_e32 v184, 0xbfb8aa3b, v144
	v_mul_f32_e32 v185, 0xbfb8aa3b, v145
	v_mul_f32_e32 v186, 0xbfb8aa3b, v146
	v_mul_f32_e32 v187, 0xbfb8aa3b, v147
	v_mul_f32_e32 v198, 0xbfb8aa3b, v148
	v_mul_f32_e32 v199, 0xbfb8aa3b, v149
	v_mul_f32_e32 v200, 0xbfb8aa3b, v150
	v_mul_f32_e32 v201, 0xbfb8aa3b, v151
	v_mul_f32_e32 v202, 0xbfb8aa3b, v152
	v_mul_f32_e32 v203, 0xbfb8aa3b, v153
	v_mul_f32_e32 v204, 0xbfb8aa3b, v154
	v_mul_f32_e32 v205, 0xbfb8aa3b, v155
	v_exp_f32_e32 v180, v180
	v_exp_f32_e32 v181, v181
	v_exp_f32_e32 v182, v182
	v_exp_f32_e32 v183, v183
	v_exp_f32_e32 v184, v184
	v_exp_f32_e32 v185, v185
	v_exp_f32_e32 v186, v186
	v_exp_f32_e32 v187, v187
	v_exp_f32_e32 v198, v198
	v_exp_f32_e32 v199, v199
	v_exp_f32_e32 v200, v200
	v_exp_f32_e32 v201, v201
	v_exp_f32_e32 v202, v202
	v_exp_f32_e32 v203, v203
	v_exp_f32_e32 v204, v204
	v_exp_f32_e32 v205, v205
	v_mul_f32_e32 v56, v56, v172
	v_mul_f32_e32 v57, v57, v172
	v_mul_f32_e32 v58, v58, v172
	v_mul_f32_e32 v59, v59, v172
	v_mul_f32_e32 v60, v60, v172
	v_mul_f32_e32 v61, v61, v172
	v_mul_f32_e32 v62, v62, v172
	v_mul_f32_e32 v63, v63, v172
	v_mul_f32_e32 v64, v64, v172
	v_mul_f32_e32 v65, v65, v172
	v_mul_f32_e32 v66, v66, v172
	v_mul_f32_e32 v67, v67, v172
	v_mul_f32_e32 v68, v68, v172
	v_mul_f32_e32 v69, v69, v172
	v_mul_f32_e32 v70, v70, v172
	v_mul_f32_e32 v71, v71, v172
	v_add_f32_e32 v180, 1.0, v180
	v_add_f32_e32 v181, 1.0, v181
	v_add_f32_e32 v182, 1.0, v182
	v_add_f32_e32 v183, 1.0, v183
	v_add_f32_e32 v184, 1.0, v184
	v_add_f32_e32 v185, 1.0, v185
	v_add_f32_e32 v186, 1.0, v186
	v_add_f32_e32 v187, 1.0, v187
	v_add_f32_e32 v198, 1.0, v198
	v_add_f32_e32 v199, 1.0, v199
	v_add_f32_e32 v200, 1.0, v200
	v_add_f32_e32 v201, 1.0, v201
	v_add_f32_e32 v202, 1.0, v202
	v_add_f32_e32 v203, 1.0, v203
	v_add_f32_e32 v204, 1.0, v204
	v_add_f32_e32 v205, 1.0, v205
	v_rcp_f32_e32 v180, v180
	v_rcp_f32_e32 v181, v181
	v_rcp_f32_e32 v182, v182
	v_rcp_f32_e32 v183, v183
	v_rcp_f32_e32 v184, v184
	v_rcp_f32_e32 v185, v185
	v_rcp_f32_e32 v186, v186
	v_rcp_f32_e32 v187, v187
	v_rcp_f32_e32 v198, v198
	v_rcp_f32_e32 v199, v199
	v_rcp_f32_e32 v200, v200
	v_rcp_f32_e32 v201, v201
	v_rcp_f32_e32 v202, v202
	v_rcp_f32_e32 v203, v203
	v_rcp_f32_e32 v204, v204
	v_rcp_f32_e32 v205, v205
	v_mul_f32_e32 v56, v56, v140
	v_mul_f32_e32 v57, v57, v141
	v_mul_f32_e32 v58, v58, v142
	v_mul_f32_e32 v59, v59, v143
	v_mul_f32_e32 v60, v60, v144
	v_mul_f32_e32 v61, v61, v145
	v_mul_f32_e32 v62, v62, v146
	v_mul_f32_e32 v63, v63, v147
	v_mul_f32_e32 v64, v64, v148
	v_mul_f32_e32 v65, v65, v149
	v_mul_f32_e32 v66, v66, v150
	v_mul_f32_e32 v67, v67, v151
	v_mul_f32_e32 v68, v68, v152
	v_mul_f32_e32 v69, v69, v153
	v_mul_f32_e32 v70, v70, v154
	v_mul_f32_e32 v71, v71, v155
	v_mul_f32_e32 v56, v56, v180
	v_mul_f32_e32 v57, v57, v181
	v_mul_f32_e32 v58, v58, v182
	v_mul_f32_e32 v59, v59, v183
	v_mul_f32_e32 v60, v60, v184
	v_mul_f32_e32 v61, v61, v185
	v_mul_f32_e32 v62, v62, v186
	v_mul_f32_e32 v63, v63, v187
	v_mul_f32_e32 v64, v64, v198
	v_mul_f32_e32 v65, v65, v199
	v_mul_f32_e32 v66, v66, v200
	v_mul_f32_e32 v67, v67, v201
	v_mul_f32_e32 v68, v68, v202
	v_mul_f32_e32 v69, v69, v203
	v_mul_f32_e32 v70, v70, v204
	v_mul_f32_e32 v71, v71, v205
	v_cvt_pk_bf16_f32 v164, v56, v57
	v_cvt_pk_bf16_f32 v165, v58, v59
	v_cvt_pk_bf16_f32 v166, v60, v61
	v_cvt_pk_bf16_f32 v167, v62, v63
	v_cvt_pk_bf16_f32 v168, v64, v65
	v_cvt_pk_bf16_f32 v169, v66, v67
	v_cvt_pk_bf16_f32 v170, v68, v69
	v_cvt_pk_bf16_f32 v171, v70, v71
	s_add_i32 s5, s41, s54
	s_add_i32 s5, s5, 6
	s_lshl_b32 s5, s5, 17
	s_add_u32 s0, s58, s5
	s_addc_u32 s1, s59, 0
	global_store_dwordx4 v196, v[164:167], s[0:1]
	global_store_dwordx4 v196, v[168:171], s[0:1] offset:16
	s_nop 1
